# in-proj epilogue: bf16 store pairs widened to 16-byte stores via v_permlane16_swap (64 B per row per instruction)
# speedup vs baseline: 1.0461x; 1.0119x over previous
.LBB0_361:
	v_mbcnt_lo_u32_b32 v226, -1, 0
	v_mbcnt_hi_u32_b32 v226, -1, v226
	v_and_b32_e32 v226, 16, v226
	v_lshrrev_b32_e32 v227, 1, v226
	v_add_u32_e32 v226, v226, v227
	v_mov_b32_e32 v227, 0
	v_mov_b32_e32 v137, v150
	v_mov_b32_e32 v158, v151
	s_lshl_b32 s4, s40, 8
	v_lshl_add_u32 v148, v158, 4, v137
	s_add_i32 s4, s4, s74
	v_lshlrev_b32_e32 v156, 2, v148
	v_add_u32_e32 v136, s4, v137
	v_xor_b32_e32 v155, 64, v156
	s_cmp_lt_i32 s41, 9
	v_xor_b32_e32 v154, 0x80, v156
	s_cbranch_scc1 .LBB0_432
	s_mov_b64 s[60:61], 0
	s_cmp_eq_u32 s41, 9
	s_mov_b64 s[4:5], 0
	s_cbranch_scc0 .LBB0_378
	v_mul_f32_e32 v137, v127, v127
	v_mul_f32_e32 v138, v129, v129
	v_fmac_f32_e32 v137, v126, v126
	v_fmac_f32_e32 v138, v128, v128
	v_add_f32_e32 v137, v137, v138
	v_mul_f32_e32 v138, v123, v123
	v_mul_f32_e32 v139, v125, v125
	v_fmac_f32_e32 v138, v122, v122
	v_fmac_f32_e32 v139, v124, v124
	v_add_f32_e32 v138, v138, v139
	v_add_f32_e32 v137, v137, v138
	ds_bpermute_b32 v138, v155, v137
	v_cmp_eq_u32_e64 s[4:5], 0, v158
	s_waitcnt lgkmcnt(0)
	v_add_f32_e32 v137, v137, v138
	ds_bpermute_b32 v138, v154, v137
	s_and_saveexec_b64 s[62:63], s[4:5]
	s_cbranch_execz .LBB0_365
	s_waitcnt lgkmcnt(0)
	v_add_f32_e32 v140, v137, v138
	v_ashrrev_i32_e32 v137, 31, v136
	v_lshl_add_u64 v[138:139], v[136:137], 4, s[12:13]
	global_store_dword v[138:139], v140, off

.LBB0_381:
	s_or_b64 exec, exec, s[60:61]
	v_lshlrev_b32_e32 v138, 2, v158
	s_waitcnt lgkmcnt(0)
	v_ashrrev_i32_e32 v139, 31, v138
	s_lshl_b32 s25, s41, 8
	v_lshlrev_b64 v[146:147], 2, v[138:139]
	s_or_b32 s55, s25, s34
	v_lshl_add_u64 v[144:145], s[78:79], 0, v[146:147]
	v_lshl_add_u64 v[142:143], s[80:81], 0, v[146:147]
	v_lshl_add_u64 v[140:141], v[138:139], 1, s[76:77]
	v_add_u32_e32 v139, 0xfffff800, v138
	v_cmp_eq_u32_e64 s[4:5], 0, v148
	s_cmpk_gt_i32 s55, 0x5ff
	s_mov_b64 s[60:61], -1
	s_cbranch_scc0 .LBB0_397
	s_cmpk_lt_u32 s25, 0x800
	s_cselect_b64 s[60:61], -1, 0
	s_add_i32 s16, s55, 0xfffff660
	s_cmpk_lt_u32 s16, 0x200
	s_cselect_b64 s[16:17], -1, 0
	s_or_b64 s[16:17], s[60:61], s[16:17]
	s_andn2_b64 vcc, exec, s[16:17]
	s_mov_b64 s[62:63], -1
	s_cbranch_vccz .LBB0_394
	s_cmpk_gt_u32 s25, 0x8ff
	s_cbranch_scc0 .LBB0_391
	s_cmpk_gt_u32 s25, 0x97f
	s_cbranch_scc0 .LBB0_388
	s_cmpk_gt_u32 s55, 0x99f
	s_cbranch_scc1 .LBB0_387
	v_lshlrev_b64 v[148:149], 6, v[136:137]
	v_lshl_add_u64 v[160:161], v[144:145], 0, v[148:149]
	v_lshl_add_u64 v[164:165], v[142:143], 0, v[148:149]
	global_load_dwordx4 v[160:163], v[160:161], off
	s_mov_b64 s[16:17], 0x400
	global_load_dwordx4 v[178:181], v[164:165], off
	s_waitcnt vmcnt(0)
	v_pk_mul_f32 v[164:165], v[124:125], v[180:181]
	v_pk_mul_f32 v[168:169], v[122:123], v[178:179]
	v_pk_mul_f32 v[170:171], v[128:129], v[180:181]
	v_pk_mul_f32 v[172:173], v[126:127], v[178:179]
	v_pk_fma_f32 v[164:165], v[128:129], v[162:163], v[164:165] neg_lo:[0,0,1] neg_hi:[0,0,1]
	v_pk_fma_f32 v[168:169], v[126:127], v[160:161], v[168:169] neg_lo:[0,0,1] neg_hi:[0,0,1]
	v_pk_fma_f32 v[162:163], v[124:125], v[162:163], v[170:171]
	v_pk_fma_f32 v[160:161], v[122:123], v[160:161], v[172:173]
	v_lshl_add_u64 v[170:171], v[140:141], 0, v[148:149]
	v_cvt_pk_bf16_f32 v228, v168, v169
	v_cvt_pk_bf16_f32 v229, v164, v165
	v_cvt_pk_bf16_f32 v230, v160, v161
	v_cvt_pk_bf16_f32 v231, v162, v163
	v_lshl_add_u64 v[164:165], v[148:149], 0, s[16:17]
	s_nop 1
	v_permlane16_swap_b32_e32 v228, v230
	v_permlane16_swap_b32_e32 v229, v231
	v_lshl_add_u64 v[214:215], v[170:171], 0, v[226:227]
	global_store_dwordx4 v[214:215], v[228:231], off
	v_lshl_add_u64 v[160:161], v[144:145], 0, v[164:165]
	v_lshl_add_u64 v[168:169], v[142:143], 0, v[164:165]
	global_load_dwordx4 v[160:163], v[160:161], off
	v_lshl_add_u64 v[164:165], v[140:141], 0, v[164:165]
	global_load_dwordx4 v[178:181], v[168:169], off
	s_mov_b64 s[16:17], 0xc00
	s_waitcnt vmcnt(0)
	v_pk_mul_f32 v[168:169], v[116:117], v[180:181]
	v_pk_mul_f32 v[170:171], v[114:115], v[178:179]
	v_pk_mul_f32 v[172:173], v[120:121], v[180:181]
	v_pk_mul_f32 v[174:175], v[118:119], v[178:179]
	v_pk_fma_f32 v[168:169], v[120:121], v[162:163], v[168:169] neg_lo:[0,0,1] neg_hi:[0,0,1]
	v_pk_fma_f32 v[170:171], v[118:119], v[160:161], v[170:171] neg_lo:[0,0,1] neg_hi:[0,0,1]
	v_pk_fma_f32 v[162:163], v[116:117], v[162:163], v[172:173]
	v_pk_fma_f32 v[160:161], v[114:115], v[160:161], v[174:175]
	v_cvt_pk_bf16_f32 v232, v170, v171
	v_cvt_pk_bf16_f32 v233, v168, v169
	v_cvt_pk_bf16_f32 v234, v160, v161
	v_cvt_pk_bf16_f32 v235, v162, v163
	s_nop 1
	v_permlane16_swap_b32_e32 v232, v234
	v_permlane16_swap_b32_e32 v233, v235
	v_lshl_add_u64 v[216:217], v[164:165], 0, v[226:227]
	global_store_dwordx4 v[216:217], v[232:235], off
	v_lshl_add_u64 v[164:165], v[148:149], 0, s[36:37]
	v_lshl_add_u64 v[160:161], v[144:145], 0, v[164:165]
	v_lshl_add_u64 v[168:169], v[142:143], 0, v[164:165]
	global_load_dwordx4 v[160:163], v[160:161], off
	v_lshl_add_u64 v[164:165], v[140:141], 0, v[164:165]
	global_load_dwordx4 v[178:181], v[168:169], off
	s_waitcnt vmcnt(0)
	v_pk_mul_f32 v[168:169], v[108:109], v[180:181]
	v_pk_mul_f32 v[170:171], v[106:107], v[178:179]
	v_pk_mul_f32 v[172:173], v[112:113], v[180:181]
	v_pk_mul_f32 v[174:175], v[110:111], v[178:179]
	v_pk_fma_f32 v[168:169], v[112:113], v[162:163], v[168:169] neg_lo:[0,0,1] neg_hi:[0,0,1]
	v_pk_fma_f32 v[170:171], v[110:111], v[160:161], v[170:171] neg_lo:[0,0,1] neg_hi:[0,0,1]
	v_pk_fma_f32 v[162:163], v[108:109], v[162:163], v[172:173]
	v_pk_fma_f32 v[160:161], v[106:107], v[160:161], v[174:175]
	v_cvt_pk_bf16_f32 v236, v170, v171
	v_cvt_pk_bf16_f32 v237, v168, v169
	v_cvt_pk_bf16_f32 v238, v160, v161
	v_cvt_pk_bf16_f32 v239, v162, v163
	s_nop 1
	v_permlane16_swap_b32_e32 v236, v238
	v_permlane16_swap_b32_e32 v237, v239
	v_lshl_add_u64 v[218:219], v[164:165], 0, v[226:227]
	global_store_dwordx4 v[218:219], v[236:239], off
	v_lshl_add_u64 v[164:165], v[148:149], 0, s[16:17]
	v_lshl_add_u64 v[160:161], v[144:145], 0, v[164:165]
	v_lshl_add_u64 v[168:169], v[142:143], 0, v[164:165]
	global_load_dwordx4 v[160:163], v[160:161], off
	v_lshl_add_u64 v[164:165], v[140:141], 0, v[164:165]
	global_load_dwordx4 v[178:181], v[168:169], off
	s_mov_b64 s[16:17], 0x2400
	s_waitcnt vmcnt(0)
	v_pk_mul_f32 v[168:169], v[100:101], v[180:181]
	v_pk_mul_f32 v[170:171], v[98:99], v[178:179]
	v_pk_mul_f32 v[172:173], v[104:105], v[180:181]
	v_pk_mul_f32 v[174:175], v[102:103], v[178:179]
	v_pk_fma_f32 v[168:169], v[104:105], v[162:163], v[168:169] neg_lo:[0,0,1] neg_hi:[0,0,1]
	v_pk_fma_f32 v[170:171], v[102:103], v[160:161], v[170:171] neg_lo:[0,0,1] neg_hi:[0,0,1]
	v_pk_fma_f32 v[162:163], v[100:101], v[162:163], v[172:173]
	v_pk_fma_f32 v[160:161], v[98:99], v[160:161], v[174:175]
	v_cvt_pk_bf16_f32 v240, v170, v171
	v_cvt_pk_bf16_f32 v241, v168, v169
	v_cvt_pk_bf16_f32 v242, v160, v161
	v_cvt_pk_bf16_f32 v243, v162, v163
	s_nop 1
	v_permlane16_swap_b32_e32 v240, v242
	v_permlane16_swap_b32_e32 v241, v243
	v_lshl_add_u64 v[214:215], v[164:165], 0, v[226:227]
	global_store_dwordx4 v[214:215], v[240:243], off
	v_lshl_add_u64 v[164:165], v[148:149], 0, s[68:69]
	v_lshl_add_u64 v[160:161], v[144:145], 0, v[164:165]
	v_lshl_add_u64 v[168:169], v[142:143], 0, v[164:165]
	global_load_dwordx4 v[160:163], v[160:161], off
	v_lshl_add_u64 v[164:165], v[140:141], 0, v[164:165]
	global_load_dwordx4 v[178:181], v[168:169], off
	s_waitcnt vmcnt(0)
	v_pk_mul_f32 v[168:169], v[92:93], v[180:181]
	v_pk_mul_f32 v[170:171], v[90:91], v[178:179]
	v_pk_mul_f32 v[172:173], v[96:97], v[180:181]
	v_pk_mul_f32 v[174:175], v[94:95], v[178:179]
	v_pk_fma_f32 v[168:169], v[96:97], v[162:163], v[168:169] neg_lo:[0,0,1] neg_hi:[0,0,1]
	v_pk_fma_f32 v[170:171], v[94:95], v[160:161], v[170:171] neg_lo:[0,0,1] neg_hi:[0,0,1]
	v_pk_fma_f32 v[162:163], v[92:93], v[162:163], v[172:173]
	v_pk_fma_f32 v[160:161], v[90:91], v[160:161], v[174:175]
	v_cvt_pk_bf16_f32 v244, v170, v171
	v_cvt_pk_bf16_f32 v245, v168, v169
	v_cvt_pk_bf16_f32 v246, v160, v161
	v_cvt_pk_bf16_f32 v247, v162, v163
	s_nop 1
	v_permlane16_swap_b32_e32 v244, v246
	v_permlane16_swap_b32_e32 v245, v247
	v_lshl_add_u64 v[216:217], v[164:165], 0, v[226:227]
	global_store_dwordx4 v[216:217], v[244:247], off
	v_lshl_add_u64 v[164:165], v[148:149], 0, s[16:17]
	v_lshl_add_u64 v[160:161], v[144:145], 0, v[164:165]
	v_lshl_add_u64 v[168:169], v[142:143], 0, v[164:165]
	global_load_dwordx4 v[160:163], v[160:161], off
	v_lshl_add_u64 v[164:165], v[140:141], 0, v[164:165]
	global_load_dwordx4 v[178:181], v[168:169], off
	s_mov_b64 s[16:17], 0x2800
	s_waitcnt vmcnt(0)
	v_pk_mul_f32 v[168:169], v[84:85], v[180:181]
	v_pk_mul_f32 v[170:171], v[82:83], v[178:179]
	v_pk_mul_f32 v[172:173], v[88:89], v[180:181]
	v_pk_mul_f32 v[174:175], v[86:87], v[178:179]
	v_pk_fma_f32 v[168:169], v[88:89], v[162:163], v[168:169] neg_lo:[0,0,1] neg_hi:[0,0,1]
	v_pk_fma_f32 v[170:171], v[86:87], v[160:161], v[170:171] neg_lo:[0,0,1] neg_hi:[0,0,1]
	v_pk_fma_f32 v[162:163], v[84:85], v[162:163], v[172:173]
	v_pk_fma_f32 v[160:161], v[82:83], v[160:161], v[174:175]
	v_cvt_pk_bf16_f32 v248, v170, v171
	v_cvt_pk_bf16_f32 v249, v168, v169
	v_cvt_pk_bf16_f32 v250, v160, v161
	v_cvt_pk_bf16_f32 v251, v162, v163
	s_nop 1
	v_permlane16_swap_b32_e32 v248, v250
	v_permlane16_swap_b32_e32 v249, v251
	v_lshl_add_u64 v[218:219], v[164:165], 0, v[226:227]
	global_store_dwordx4 v[218:219], v[248:251], off
	v_lshl_add_u64 v[164:165], v[148:149], 0, s[16:17]
	v_lshl_add_u64 v[160:161], v[144:145], 0, v[164:165]
	v_lshl_add_u64 v[168:169], v[142:143], 0, v[164:165]
	global_load_dwordx4 v[160:163], v[160:161], off
	s_mov_b64 s[16:17], 0x2c00
	global_load_dwordx4 v[178:181], v[168:169], off
	v_lshl_add_u64 v[164:165], v[140:141], 0, v[164:165]
	v_lshl_add_u64 v[148:149], v[148:149], 0, s[16:17]
	s_waitcnt vmcnt(0)
	v_pk_mul_f32 v[168:169], v[76:77], v[180:181]
	v_pk_mul_f32 v[170:171], v[74:75], v[178:179]
	v_pk_mul_f32 v[172:173], v[80:81], v[180:181]
	v_pk_mul_f32 v[174:175], v[78:79], v[178:179]
	v_pk_fma_f32 v[168:169], v[80:81], v[162:163], v[168:169] neg_lo:[0,0,1] neg_hi:[0,0,1]
	v_pk_fma_f32 v[170:171], v[78:79], v[160:161], v[170:171] neg_lo:[0,0,1] neg_hi:[0,0,1]
	v_pk_fma_f32 v[162:163], v[76:77], v[162:163], v[172:173]
	v_pk_fma_f32 v[160:161], v[74:75], v[160:161], v[174:175]
	v_cvt_pk_bf16_f32 v228, v170, v171
	v_cvt_pk_bf16_f32 v229, v168, v169
	v_cvt_pk_bf16_f32 v230, v160, v161
	v_cvt_pk_bf16_f32 v231, v162, v163
	s_nop 1
	v_permlane16_swap_b32_e32 v228, v230
	v_permlane16_swap_b32_e32 v229, v231
	v_lshl_add_u64 v[214:215], v[164:165], 0, v[226:227]
	global_store_dwordx4 v[214:215], v[228:231], off
	v_lshl_add_u64 v[160:161], v[144:145], 0, v[148:149]
	v_lshl_add_u64 v[164:165], v[142:143], 0, v[148:149]
	global_load_dwordx4 v[160:163], v[160:161], off
	v_lshl_add_u64 v[148:149], v[140:141], 0, v[148:149]
	global_load_dwordx4 v[178:181], v[164:165], off
	s_waitcnt vmcnt(0)
	v_pk_mul_f32 v[164:165], v[68:69], v[180:181]
	v_pk_mul_f32 v[168:169], v[66:67], v[178:179]
	v_pk_mul_f32 v[170:171], v[72:73], v[180:181]
	v_pk_mul_f32 v[172:173], v[70:71], v[178:179]
	v_pk_fma_f32 v[164:165], v[72:73], v[162:163], v[164:165] neg_lo:[0,0,1] neg_hi:[0,0,1]
	v_pk_fma_f32 v[168:169], v[70:71], v[160:161], v[168:169] neg_lo:[0,0,1] neg_hi:[0,0,1]
	v_pk_fma_f32 v[162:163], v[68:69], v[162:163], v[170:171]
	v_pk_fma_f32 v[160:161], v[66:67], v[160:161], v[172:173]
	v_cvt_pk_bf16_f32 v232, v168, v169
	v_cvt_pk_bf16_f32 v233, v164, v165
	v_cvt_pk_bf16_f32 v234, v160, v161
	v_cvt_pk_bf16_f32 v235, v162, v163
	s_nop 1
	v_permlane16_swap_b32_e32 v232, v234
	v_permlane16_swap_b32_e32 v233, v235
	v_lshl_add_u64 v[216:217], v[148:149], 0, v[226:227]
	global_store_dwordx4 v[216:217], v[232:235], off

.LBB0_388:
	s_andn2_b64 vcc, exec, s[62:63]
	s_cbranch_vccnz .LBB0_390
	s_add_i32 s16, s55, 0xfffff700
	v_add_u32_e32 v148, s16, v138
	v_readlane_b32 s16, v254, 5
	v_ashrrev_i32_e32 v149, 31, v148
	v_readlane_b32 s17, v254, 6
	v_lshlrev_b64 v[160:161], 8, v[136:137]
	v_cvt_pk_bf16_f32 v240, v118, v119
	v_lshl_add_u64 v[148:149], v[148:149], 1, s[16:17]
	v_lshl_add_u64 v[148:149], v[148:149], 0, v[160:161]
	v_cvt_pk_bf16_f32 v236, v126, v127
	v_cvt_pk_bf16_f32 v237, v128, v129
	v_cvt_pk_bf16_f32 v238, v122, v123
	v_cvt_pk_bf16_f32 v239, v124, v125
	s_mov_b64 s[16:17], 0x1000
	s_nop 1
	v_permlane16_swap_b32_e32 v236, v238
	v_permlane16_swap_b32_e32 v237, v239
	v_lshl_add_u64 v[218:219], v[148:149], 0, v[226:227]
	global_store_dwordx4 v[218:219], v[236:239], off
	v_lshl_add_u64 v[160:161], v[148:149], 0, s[16:17]
	s_movk_i32 s16, 0x2000
	v_add_co_u32_e32 v164, vcc, s16, v148
	v_cvt_pk_bf16_f32 v241, v120, v121
	s_nop 0
	v_addc_co_u32_e32 v165, vcc, 0, v149, vcc
	v_cvt_pk_bf16_f32 v242, v114, v115
	v_cvt_pk_bf16_f32 v243, v116, v117
	s_nop 1
	v_permlane16_swap_b32_e32 v240, v242
	v_permlane16_swap_b32_e32 v241, v243
	v_lshl_add_u64 v[214:215], v[160:161], 0, v[226:227]
	global_store_dwordx4 v[214:215], v[240:243], off
	v_cvt_pk_bf16_f32 v244, v110, v111
	v_cvt_pk_bf16_f32 v245, v112, v113
	v_lshl_add_u64 v[160:161], v[148:149], 0, s[68:69]
	v_cvt_pk_bf16_f32 v246, v106, v107
	v_cvt_pk_bf16_f32 v247, v108, v109
	s_mov_b64 s[16:17], 0x3000
	s_nop 1
	v_permlane16_swap_b32_e32 v244, v246
	v_permlane16_swap_b32_e32 v245, v247
	v_lshl_add_u64 v[216:217], v[160:161], 0, v[226:227]
	global_store_dwordx4 v[216:217], v[244:247], off
	v_lshl_add_u64 v[160:161], v[148:149], 0, s[16:17]
	s_movk_i32 s16, 0x3000
	v_add_co_u32_e32 v164, vcc, s16, v148
	v_cvt_pk_bf16_f32 v248, v102, v103
	v_cvt_pk_bf16_f32 v249, v104, v105
	v_addc_co_u32_e32 v165, vcc, 0, v149, vcc
	v_cvt_pk_bf16_f32 v250, v98, v99
	v_cvt_pk_bf16_f32 v251, v100, v101
	s_mov_b64 s[16:17], 0x8000
	s_nop 1
	v_permlane16_swap_b32_e32 v248, v250
	v_permlane16_swap_b32_e32 v249, v251
	v_lshl_add_u64 v[218:219], v[160:161], 0, v[226:227]
	global_store_dwordx4 v[218:219], v[248:251], off
	v_lshl_add_u64 v[160:161], v[148:149], 0, s[16:17]
	s_mov_b32 s16, 0x9000
	v_add_co_u32_e32 v164, vcc, s16, v148
	v_cvt_pk_bf16_f32 v228, v94, v95
	v_cvt_pk_bf16_f32 v229, v96, v97
	v_addc_co_u32_e32 v165, vcc, 0, v149, vcc
	v_cvt_pk_bf16_f32 v230, v90, v91
	v_cvt_pk_bf16_f32 v231, v92, v93
	s_nop 1
	v_permlane16_swap_b32_e32 v228, v230
	v_permlane16_swap_b32_e32 v229, v231
	v_lshl_add_u64 v[214:215], v[160:161], 0, v[226:227]
	global_store_dwordx4 v[214:215], v[228:231], off
	s_mov_b64 s[16:17], 0x9000
	v_cvt_pk_bf16_f32 v232, v86, v87
	v_cvt_pk_bf16_f32 v233, v88, v89
	v_lshl_add_u64 v[160:161], v[148:149], 0, s[16:17]
	v_cvt_pk_bf16_f32 v234, v82, v83
	v_cvt_pk_bf16_f32 v235, v84, v85
	s_mov_b64 s[16:17], 0xa000
	s_nop 1
	v_permlane16_swap_b32_e32 v232, v234
	v_permlane16_swap_b32_e32 v233, v235
	v_lshl_add_u64 v[216:217], v[160:161], 0, v[226:227]
	global_store_dwordx4 v[216:217], v[232:235], off
	v_lshl_add_u64 v[160:161], v[148:149], 0, s[16:17]
	s_mov_b32 s16, 0xa000
	v_add_co_u32_e32 v164, vcc, s16, v148
	v_cvt_pk_bf16_f32 v236, v78, v79
	v_cvt_pk_bf16_f32 v237, v80, v81
	v_addc_co_u32_e32 v165, vcc, 0, v149, vcc
	v_cvt_pk_bf16_f32 v238, v74, v75
	v_cvt_pk_bf16_f32 v239, v76, v77
	s_mov_b64 s[16:17], 0xb000
	s_nop 1
	v_permlane16_swap_b32_e32 v236, v238
	v_permlane16_swap_b32_e32 v237, v239
	v_lshl_add_u64 v[218:219], v[160:161], 0, v[226:227]
	global_store_dwordx4 v[218:219], v[236:239], off
	v_lshl_add_u64 v[160:161], v[148:149], 0, s[16:17]
	v_add_co_u32_e32 v148, vcc, 0xb000, v148
	v_cvt_pk_bf16_f32 v240, v70, v71
	v_cvt_pk_bf16_f32 v241, v72, v73
	v_addc_co_u32_e32 v149, vcc, 0, v149, vcc
	v_cvt_pk_bf16_f32 v242, v66, v67
	v_cvt_pk_bf16_f32 v243, v68, v69
	s_nop 1
	v_permlane16_swap_b32_e32 v240, v242
	v_permlane16_swap_b32_e32 v241, v243
	v_lshl_add_u64 v[214:215], v[160:161], 0, v[226:227]
	global_store_dwordx4 v[214:215], v[240:243], off

.LBB0_391:
	s_andn2_b64 vcc, exec, s[62:63]
	s_cbranch_vccnz .LBB0_393
	v_add_u32_e32 v148, s55, v139
	v_ashrrev_i32_e32 v149, 31, v148
	v_lshl_add_u64 v[148:149], v[148:149], 1, s[44:45]
	v_lshlrev_b64 v[160:161], 9, v[136:137]
	v_lshl_add_u64 v[148:149], v[148:149], 0, v[160:161]
	s_movk_i32 s16, 0x2000
	v_cvt_pk_bf16_f32 v244, v126, v127
	v_cvt_pk_bf16_f32 v245, v128, v129
	v_add_co_u32_e32 v164, vcc, s16, v148
	v_cvt_pk_bf16_f32 v246, v122, v123
	v_cvt_pk_bf16_f32 v247, v124, v125
	v_cvt_pk_bf16_f32 v248, v118, v119
	v_cvt_pk_bf16_f32 v249, v120, v121
	v_addc_co_u32_e32 v165, vcc, 0, v149, vcc
	s_nop 1
	v_permlane16_swap_b32_e32 v244, v246
	v_permlane16_swap_b32_e32 v245, v247
	v_lshl_add_u64 v[216:217], v[148:149], 0, v[226:227]
	global_store_dwordx4 v[216:217], v[244:247], off
	v_lshl_add_u64 v[160:161], v[148:149], 0, s[68:69]
	v_cvt_pk_bf16_f32 v250, v114, v115
	v_cvt_pk_bf16_f32 v251, v116, v117
	s_mov_b64 s[16:17], 0x4000
	s_nop 1
	v_permlane16_swap_b32_e32 v248, v250
	v_permlane16_swap_b32_e32 v249, v251
	v_lshl_add_u64 v[218:219], v[160:161], 0, v[226:227]
	global_store_dwordx4 v[218:219], v[248:251], off
	v_lshl_add_u64 v[160:161], v[148:149], 0, s[16:17]
	s_movk_i32 s16, 0x4000
	v_add_co_u32_e32 v164, vcc, s16, v148
	v_cvt_pk_bf16_f32 v228, v110, v111
	v_cvt_pk_bf16_f32 v229, v112, v113
	v_addc_co_u32_e32 v165, vcc, 0, v149, vcc
	v_cvt_pk_bf16_f32 v230, v106, v107
	v_cvt_pk_bf16_f32 v231, v108, v109
	s_mov_b64 s[16:17], 0x6000
	s_nop 1
	v_permlane16_swap_b32_e32 v228, v230
	v_permlane16_swap_b32_e32 v229, v231
	v_lshl_add_u64 v[214:215], v[160:161], 0, v[226:227]
	global_store_dwordx4 v[214:215], v[228:231], off
	v_lshl_add_u64 v[160:161], v[148:149], 0, s[16:17]
	s_movk_i32 s16, 0x6000
	v_add_co_u32_e32 v164, vcc, s16, v148
	v_cvt_pk_bf16_f32 v232, v102, v103
	v_cvt_pk_bf16_f32 v233, v104, v105
	v_addc_co_u32_e32 v165, vcc, 0, v149, vcc
	v_cvt_pk_bf16_f32 v234, v98, v99
	v_cvt_pk_bf16_f32 v235, v100, v101
	s_mov_b64 s[16:17], 0x10000
	s_nop 1
	v_permlane16_swap_b32_e32 v232, v234
	v_permlane16_swap_b32_e32 v233, v235
	v_lshl_add_u64 v[216:217], v[160:161], 0, v[226:227]
	global_store_dwordx4 v[216:217], v[232:235], off
	v_lshl_add_u64 v[160:161], v[148:149], 0, s[16:17]
	s_mov_b32 s16, 0x10000
	v_add_co_u32_e32 v164, vcc, s16, v148
	v_cvt_pk_bf16_f32 v236, v94, v95
	v_cvt_pk_bf16_f32 v237, v96, v97
	v_addc_co_u32_e32 v165, vcc, 0, v149, vcc
	v_cvt_pk_bf16_f32 v238, v90, v91
	v_cvt_pk_bf16_f32 v239, v92, v93
	s_mov_b64 s[16:17], 0x12000
	s_nop 1
	v_permlane16_swap_b32_e32 v236, v238
	v_permlane16_swap_b32_e32 v237, v239
	v_lshl_add_u64 v[218:219], v[160:161], 0, v[226:227]
	global_store_dwordx4 v[218:219], v[236:239], off
	v_lshl_add_u64 v[160:161], v[148:149], 0, s[16:17]
	s_mov_b32 s16, 0x12000
	v_add_co_u32_e32 v164, vcc, s16, v148
	v_cvt_pk_bf16_f32 v240, v86, v87
	v_cvt_pk_bf16_f32 v241, v88, v89
	v_addc_co_u32_e32 v165, vcc, 0, v149, vcc
	v_cvt_pk_bf16_f32 v242, v82, v83
	v_cvt_pk_bf16_f32 v243, v84, v85
	s_mov_b64 s[16:17], 0x14000
	s_nop 1
	v_permlane16_swap_b32_e32 v240, v242
	v_permlane16_swap_b32_e32 v241, v243
	v_lshl_add_u64 v[214:215], v[160:161], 0, v[226:227]
	global_store_dwordx4 v[214:215], v[240:243], off
	v_lshl_add_u64 v[160:161], v[148:149], 0, s[16:17]
	s_mov_b32 s16, 0x14000
	v_add_co_u32_e32 v164, vcc, s16, v148
	v_cvt_pk_bf16_f32 v244, v78, v79
	v_cvt_pk_bf16_f32 v245, v80, v81
	v_addc_co_u32_e32 v165, vcc, 0, v149, vcc
	v_cvt_pk_bf16_f32 v246, v74, v75
	v_cvt_pk_bf16_f32 v247, v76, v77
	s_mov_b64 s[16:17], 0x16000
	s_nop 1
	v_permlane16_swap_b32_e32 v244, v246
	v_permlane16_swap_b32_e32 v245, v247
	v_lshl_add_u64 v[216:217], v[160:161], 0, v[226:227]
	global_store_dwordx4 v[216:217], v[244:247], off
	v_lshl_add_u64 v[160:161], v[148:149], 0, s[16:17]
	v_add_co_u32_e32 v148, vcc, 0x16000, v148
	v_cvt_pk_bf16_f32 v248, v70, v71
	v_cvt_pk_bf16_f32 v249, v72, v73
	v_addc_co_u32_e32 v149, vcc, 0, v149, vcc
	v_cvt_pk_bf16_f32 v250, v66, v67
	v_cvt_pk_bf16_f32 v251, v68, v69
	s_nop 1
	v_permlane16_swap_b32_e32 v248, v250
	v_permlane16_swap_b32_e32 v249, v251
	v_lshl_add_u64 v[218:219], v[160:161], 0, v[226:227]
	global_store_dwordx4 v[218:219], v[248:251], off

.LBB0_394:
	s_andn2_b64 vcc, exec, s[62:63]
	s_cbranch_vccnz .LBB0_396
	s_and_b64 s[16:17], s[60:61], exec
	s_movk_i32 s16, 0xfa00
	v_mul_f32_e32 v157, 0xbfb8aa3b, v126
	s_cselect_b32 s16, s16, 0xfffff860
	v_exp_f32_e32 v157, v157
	s_add_i32 s16, s16, s55
	v_add_u32_e32 v148, s16, v138
	v_readlane_b32 s16, v253, 38
	v_ashrrev_i32_e32 v149, 31, v148
	v_readlane_b32 s17, v253, 39
	v_lshlrev_b64 v[160:161], 11, v[136:137]
	v_add_f32_e32 v157, 1.0, v157
	v_lshl_add_u64 v[148:149], v[148:149], 1, s[16:17]
	v_lshl_add_u64 v[148:149], v[148:149], 0, v[160:161]
	v_rcp_f32_e32 v160, v157
	v_mul_f32_e32 v157, 0xbfb8aa3b, v127
	v_exp_f32_e32 v157, v157
	s_mov_b64 s[16:17], 0x8000
	v_add_f32_e32 v157, 1.0, v157
	v_rcp_f32_e32 v161, v157
	v_mul_f32_e32 v157, 0xbfb8aa3b, v128
	v_exp_f32_e32 v157, v157
	v_pk_mul_f32 v[160:161], v[126:127], v[160:161]
	s_nop 0
	v_cvt_pk_bf16_f32 v228, v160, v161
	v_add_f32_e32 v157, 1.0, v157
	v_rcp_f32_e32 v162, v157
	v_mul_f32_e32 v157, 0xbfb8aa3b, v129
	v_exp_f32_e32 v157, v157
	s_nop 0
	v_add_f32_e32 v157, 1.0, v157
	v_rcp_f32_e32 v163, v157
	v_mul_f32_e32 v157, 0xbfb8aa3b, v122
	v_exp_f32_e32 v157, v157
	v_pk_mul_f32 v[162:163], v[128:129], v[162:163]
	s_nop 0
	v_cvt_pk_bf16_f32 v229, v162, v163
	v_add_f32_e32 v157, 1.0, v157
	v_rcp_f32_e32 v160, v157
	v_mul_f32_e32 v157, 0xbfb8aa3b, v123
	v_exp_f32_e32 v157, v157
	s_nop 0
	v_add_f32_e32 v157, 1.0, v157
	v_rcp_f32_e32 v161, v157
	v_mul_f32_e32 v157, 0xbfb8aa3b, v124
	v_exp_f32_e32 v157, v157
	v_pk_mul_f32 v[160:161], v[122:123], v[160:161]
	s_nop 0
	v_cvt_pk_bf16_f32 v230, v160, v161
	v_add_f32_e32 v157, 1.0, v157
	v_rcp_f32_e32 v162, v157
	v_mul_f32_e32 v157, 0xbfb8aa3b, v125
	v_exp_f32_e32 v157, v157
	s_nop 0
	v_add_f32_e32 v157, 1.0, v157
	v_rcp_f32_e32 v163, v157
	v_mul_f32_e32 v157, 0xbfb8aa3b, v118
	v_exp_f32_e32 v157, v157
	v_pk_mul_f32 v[162:163], v[124:125], v[162:163]
	s_nop 0
	v_cvt_pk_bf16_f32 v231, v162, v163
	v_add_f32_e32 v157, 1.0, v157
	v_rcp_f32_e32 v162, v157
	v_mul_f32_e32 v157, 0xbfb8aa3b, v119
	v_exp_f32_e32 v157, v157
	s_nop 1
	v_permlane16_swap_b32_e32 v228, v230
	v_permlane16_swap_b32_e32 v229, v231
	v_lshl_add_u64 v[214:215], v[148:149], 0, v[226:227]
	global_store_dwordx4 v[214:215], v[228:231], off
	v_lshl_add_u64 v[160:161], v[148:149], 0, s[16:17]
	s_mov_b32 s16, 0x8000
	v_add_f32_e32 v157, 1.0, v157
	v_rcp_f32_e32 v163, v157
	v_mul_f32_e32 v157, 0xbfb8aa3b, v120
	v_exp_f32_e32 v157, v157
	v_pk_mul_f32 v[162:163], v[118:119], v[162:163]
	s_nop 0
	v_cvt_pk_bf16_f32 v232, v162, v163
	v_add_f32_e32 v157, 1.0, v157
	v_rcp_f32_e32 v164, v157
	v_mul_f32_e32 v157, 0xbfb8aa3b, v121
	v_exp_f32_e32 v157, v157
	s_nop 0
	v_add_f32_e32 v157, 1.0, v157
	v_rcp_f32_e32 v165, v157
	v_mul_f32_e32 v157, 0xbfb8aa3b, v114
	v_exp_f32_e32 v157, v157
	v_pk_mul_f32 v[164:165], v[120:121], v[164:165]
	s_nop 0
	v_cvt_pk_bf16_f32 v233, v164, v165
	v_add_co_u32_e32 v164, vcc, s16, v148
	v_add_f32_e32 v157, 1.0, v157
	s_nop 0
	v_addc_co_u32_e32 v165, vcc, 0, v149, vcc
	v_rcp_f32_e32 v162, v157
	v_mul_f32_e32 v157, 0xbfb8aa3b, v115
	v_exp_f32_e32 v157, v157
	s_mov_b64 s[16:17], 0x10000
	v_add_f32_e32 v157, 1.0, v157
	v_rcp_f32_e32 v163, v157
	v_mul_f32_e32 v157, 0xbfb8aa3b, v116
	v_exp_f32_e32 v157, v157
	v_pk_mul_f32 v[162:163], v[114:115], v[162:163]
	s_nop 0
	v_cvt_pk_bf16_f32 v234, v162, v163
	v_add_f32_e32 v157, 1.0, v157
	v_rcp_f32_e32 v164, v157
	v_mul_f32_e32 v157, 0xbfb8aa3b, v117
	v_exp_f32_e32 v157, v157
	s_nop 0
	v_add_f32_e32 v157, 1.0, v157
	v_rcp_f32_e32 v165, v157
	v_mul_f32_e32 v157, 0xbfb8aa3b, v110
	v_exp_f32_e32 v157, v157
	v_pk_mul_f32 v[164:165], v[116:117], v[164:165]
	s_nop 0
	v_cvt_pk_bf16_f32 v235, v164, v165
	v_add_f32_e32 v157, 1.0, v157
	s_nop 1
	v_permlane16_swap_b32_e32 v232, v234
	v_permlane16_swap_b32_e32 v233, v235
	v_lshl_add_u64 v[216:217], v[160:161], 0, v[226:227]
	global_store_dwordx4 v[216:217], v[232:235], off
	v_rcp_f32_e32 v162, v157
	v_mul_f32_e32 v157, 0xbfb8aa3b, v111
	v_exp_f32_e32 v157, v157
	v_lshl_add_u64 v[160:161], v[148:149], 0, s[16:17]
	s_mov_b32 s16, 0x10000
	v_add_f32_e32 v157, 1.0, v157
	v_rcp_f32_e32 v163, v157
	v_mul_f32_e32 v157, 0xbfb8aa3b, v112
	v_exp_f32_e32 v157, v157
	v_pk_mul_f32 v[162:163], v[110:111], v[162:163]
	s_nop 0
	v_cvt_pk_bf16_f32 v236, v162, v163
	v_add_f32_e32 v157, 1.0, v157
	v_rcp_f32_e32 v164, v157
	v_mul_f32_e32 v157, 0xbfb8aa3b, v113
	v_exp_f32_e32 v157, v157
	s_nop 0
	v_add_f32_e32 v157, 1.0, v157
	v_rcp_f32_e32 v165, v157
	v_mul_f32_e32 v157, 0xbfb8aa3b, v106
	v_exp_f32_e32 v157, v157
	v_pk_mul_f32 v[164:165], v[112:113], v[164:165]
	s_nop 0
	v_cvt_pk_bf16_f32 v237, v164, v165
	v_add_co_u32_e32 v164, vcc, s16, v148
	v_add_f32_e32 v157, 1.0, v157
	s_nop 0
	v_addc_co_u32_e32 v165, vcc, 0, v149, vcc
	v_rcp_f32_e32 v162, v157
	v_mul_f32_e32 v157, 0xbfb8aa3b, v107
	v_exp_f32_e32 v157, v157
	s_mov_b64 s[16:17], 0x18000
	v_add_f32_e32 v157, 1.0, v157
	v_rcp_f32_e32 v163, v157
	v_mul_f32_e32 v157, 0xbfb8aa3b, v108
	v_exp_f32_e32 v157, v157
	v_pk_mul_f32 v[162:163], v[106:107], v[162:163]
	s_nop 0
	v_cvt_pk_bf16_f32 v238, v162, v163
	v_add_f32_e32 v157, 1.0, v157
	v_rcp_f32_e32 v164, v157
	v_mul_f32_e32 v157, 0xbfb8aa3b, v109
	v_exp_f32_e32 v157, v157
	s_nop 0
	v_add_f32_e32 v157, 1.0, v157
	v_rcp_f32_e32 v165, v157
	v_mul_f32_e32 v157, 0xbfb8aa3b, v102
	v_exp_f32_e32 v157, v157
	v_pk_mul_f32 v[164:165], v[108:109], v[164:165]
	s_nop 0
	v_cvt_pk_bf16_f32 v239, v164, v165
	v_add_f32_e32 v157, 1.0, v157
	s_nop 1
	v_permlane16_swap_b32_e32 v236, v238
	v_permlane16_swap_b32_e32 v237, v239
	v_lshl_add_u64 v[218:219], v[160:161], 0, v[226:227]
	global_store_dwordx4 v[218:219], v[236:239], off
	v_rcp_f32_e32 v162, v157
	v_mul_f32_e32 v157, 0xbfb8aa3b, v103
	v_exp_f32_e32 v157, v157
	v_lshl_add_u64 v[160:161], v[148:149], 0, s[16:17]
	s_mov_b32 s16, 0x18000
	v_add_f32_e32 v157, 1.0, v157
	v_rcp_f32_e32 v163, v157
	v_mul_f32_e32 v157, 0xbfb8aa3b, v104
	v_exp_f32_e32 v157, v157
	v_pk_mul_f32 v[162:163], v[102:103], v[162:163]
	s_nop 0
	v_cvt_pk_bf16_f32 v240, v162, v163
	v_add_f32_e32 v157, 1.0, v157
	v_rcp_f32_e32 v164, v157
	v_mul_f32_e32 v157, 0xbfb8aa3b, v105
	v_exp_f32_e32 v157, v157
	s_nop 0
	v_add_f32_e32 v157, 1.0, v157
	v_rcp_f32_e32 v165, v157
	v_mul_f32_e32 v157, 0xbfb8aa3b, v98
	v_exp_f32_e32 v157, v157
	v_pk_mul_f32 v[164:165], v[104:105], v[164:165]
	s_nop 0
	v_cvt_pk_bf16_f32 v241, v164, v165
	v_add_co_u32_e32 v164, vcc, s16, v148
	v_add_f32_e32 v157, 1.0, v157
	s_nop 0
	v_addc_co_u32_e32 v165, vcc, 0, v149, vcc
	v_rcp_f32_e32 v162, v157
	v_mul_f32_e32 v157, 0xbfb8aa3b, v99
	v_exp_f32_e32 v157, v157
	s_mov_b64 s[16:17], 0x40000
	v_add_f32_e32 v157, 1.0, v157
	v_rcp_f32_e32 v163, v157
	v_mul_f32_e32 v157, 0xbfb8aa3b, v100
	v_exp_f32_e32 v157, v157
	v_pk_mul_f32 v[162:163], v[98:99], v[162:163]
	s_nop 0
	v_cvt_pk_bf16_f32 v242, v162, v163
	v_add_f32_e32 v157, 1.0, v157
	v_rcp_f32_e32 v164, v157
	v_mul_f32_e32 v157, 0xbfb8aa3b, v101
	v_exp_f32_e32 v157, v157
	s_nop 0
	v_add_f32_e32 v157, 1.0, v157
	v_rcp_f32_e32 v165, v157
	v_mul_f32_e32 v157, 0xbfb8aa3b, v94
	v_exp_f32_e32 v157, v157
	v_pk_mul_f32 v[164:165], v[100:101], v[164:165]
	s_nop 0
	v_cvt_pk_bf16_f32 v243, v164, v165
	v_add_f32_e32 v157, 1.0, v157
	s_nop 1
	v_permlane16_swap_b32_e32 v240, v242
	v_permlane16_swap_b32_e32 v241, v243
	v_lshl_add_u64 v[214:215], v[160:161], 0, v[226:227]
	global_store_dwordx4 v[214:215], v[240:243], off
	v_rcp_f32_e32 v162, v157
	v_mul_f32_e32 v157, 0xbfb8aa3b, v95
	v_exp_f32_e32 v157, v157
	v_lshl_add_u64 v[160:161], v[148:149], 0, s[16:17]
	s_mov_b32 s16, 0x40000
	v_add_f32_e32 v157, 1.0, v157
	v_rcp_f32_e32 v163, v157
	v_mul_f32_e32 v157, 0xbfb8aa3b, v96
	v_exp_f32_e32 v157, v157
	v_pk_mul_f32 v[162:163], v[94:95], v[162:163]
	s_nop 0
	v_cvt_pk_bf16_f32 v244, v162, v163
	v_add_f32_e32 v157, 1.0, v157
	v_rcp_f32_e32 v164, v157
	v_mul_f32_e32 v157, 0xbfb8aa3b, v97
	v_exp_f32_e32 v157, v157
	s_nop 0
	v_add_f32_e32 v157, 1.0, v157
	v_rcp_f32_e32 v165, v157
	v_mul_f32_e32 v157, 0xbfb8aa3b, v90
	v_exp_f32_e32 v157, v157
	v_pk_mul_f32 v[164:165], v[96:97], v[164:165]
	s_nop 0
	v_cvt_pk_bf16_f32 v245, v164, v165
	v_add_co_u32_e32 v164, vcc, s16, v148
	v_add_f32_e32 v157, 1.0, v157
	s_nop 0
	v_addc_co_u32_e32 v165, vcc, 0, v149, vcc
	v_rcp_f32_e32 v162, v157
	v_mul_f32_e32 v157, 0xbfb8aa3b, v91
	v_exp_f32_e32 v157, v157
	s_mov_b64 s[16:17], 0x48000
	v_add_f32_e32 v157, 1.0, v157
	v_rcp_f32_e32 v163, v157
	v_mul_f32_e32 v157, 0xbfb8aa3b, v92
	v_exp_f32_e32 v157, v157
	v_pk_mul_f32 v[162:163], v[90:91], v[162:163]
	s_nop 0
	v_cvt_pk_bf16_f32 v246, v162, v163
	v_add_f32_e32 v157, 1.0, v157
	v_rcp_f32_e32 v164, v157
	v_mul_f32_e32 v157, 0xbfb8aa3b, v93
	v_exp_f32_e32 v157, v157
	s_nop 0
	v_add_f32_e32 v157, 1.0, v157
	v_rcp_f32_e32 v165, v157
	v_mul_f32_e32 v157, 0xbfb8aa3b, v86
	v_exp_f32_e32 v157, v157
	v_pk_mul_f32 v[164:165], v[92:93], v[164:165]
	s_nop 0
	v_cvt_pk_bf16_f32 v247, v164, v165
	v_add_f32_e32 v157, 1.0, v157
	s_nop 1
	v_permlane16_swap_b32_e32 v244, v246
	v_permlane16_swap_b32_e32 v245, v247
	v_lshl_add_u64 v[216:217], v[160:161], 0, v[226:227]
	global_store_dwordx4 v[216:217], v[244:247], off
	v_rcp_f32_e32 v162, v157
	v_mul_f32_e32 v157, 0xbfb8aa3b, v87
	v_exp_f32_e32 v157, v157
	v_lshl_add_u64 v[160:161], v[148:149], 0, s[16:17]
	s_mov_b32 s16, 0x48000
	v_add_f32_e32 v157, 1.0, v157
	v_rcp_f32_e32 v163, v157
	v_mul_f32_e32 v157, 0xbfb8aa3b, v88
	v_exp_f32_e32 v157, v157
	v_pk_mul_f32 v[162:163], v[86:87], v[162:163]
	s_nop 0
	v_cvt_pk_bf16_f32 v248, v162, v163
	v_add_f32_e32 v157, 1.0, v157
	v_rcp_f32_e32 v164, v157
	v_mul_f32_e32 v157, 0xbfb8aa3b, v89
	v_exp_f32_e32 v157, v157
	s_nop 0
	v_add_f32_e32 v157, 1.0, v157
	v_rcp_f32_e32 v165, v157
	v_mul_f32_e32 v157, 0xbfb8aa3b, v82
	v_exp_f32_e32 v157, v157
	v_pk_mul_f32 v[164:165], v[88:89], v[164:165]
	s_nop 0
	v_cvt_pk_bf16_f32 v249, v164, v165
	v_add_co_u32_e32 v164, vcc, s16, v148
	v_add_f32_e32 v157, 1.0, v157
	s_nop 0
	v_addc_co_u32_e32 v165, vcc, 0, v149, vcc
	v_rcp_f32_e32 v162, v157
	v_mul_f32_e32 v157, 0xbfb8aa3b, v83
	v_exp_f32_e32 v157, v157
	s_mov_b64 s[16:17], 0x50000
	v_add_f32_e32 v157, 1.0, v157
	v_rcp_f32_e32 v163, v157
	v_mul_f32_e32 v157, 0xbfb8aa3b, v84
	v_exp_f32_e32 v157, v157
	v_pk_mul_f32 v[162:163], v[82:83], v[162:163]
	s_nop 0
	v_cvt_pk_bf16_f32 v250, v162, v163
	v_add_f32_e32 v157, 1.0, v157
	v_rcp_f32_e32 v164, v157
	v_mul_f32_e32 v157, 0xbfb8aa3b, v85
	v_exp_f32_e32 v157, v157
	s_nop 0
	v_add_f32_e32 v157, 1.0, v157
	v_rcp_f32_e32 v165, v157
	v_mul_f32_e32 v157, 0xbfb8aa3b, v78
	v_exp_f32_e32 v157, v157
	v_pk_mul_f32 v[164:165], v[84:85], v[164:165]
	s_nop 0
	v_cvt_pk_bf16_f32 v251, v164, v165
	v_add_f32_e32 v157, 1.0, v157
	s_nop 1
	v_permlane16_swap_b32_e32 v248, v250
	v_permlane16_swap_b32_e32 v249, v251
	v_lshl_add_u64 v[218:219], v[160:161], 0, v[226:227]
	global_store_dwordx4 v[218:219], v[248:251], off
	v_rcp_f32_e32 v162, v157
	v_mul_f32_e32 v157, 0xbfb8aa3b, v79
	v_exp_f32_e32 v157, v157
	v_lshl_add_u64 v[160:161], v[148:149], 0, s[16:17]
	s_mov_b32 s16, 0x50000
	v_add_f32_e32 v157, 1.0, v157
	v_rcp_f32_e32 v163, v157
	v_mul_f32_e32 v157, 0xbfb8aa3b, v80
	v_exp_f32_e32 v157, v157
	v_pk_mul_f32 v[162:163], v[78:79], v[162:163]
	s_nop 0
	v_cvt_pk_bf16_f32 v228, v162, v163
	v_add_f32_e32 v157, 1.0, v157
	v_rcp_f32_e32 v164, v157
	v_mul_f32_e32 v157, 0xbfb8aa3b, v81
	v_exp_f32_e32 v157, v157
	s_nop 0
	v_add_f32_e32 v157, 1.0, v157
	v_rcp_f32_e32 v165, v157
	v_mul_f32_e32 v157, 0xbfb8aa3b, v74
	v_exp_f32_e32 v157, v157
	v_pk_mul_f32 v[164:165], v[80:81], v[164:165]
	s_nop 0
	v_cvt_pk_bf16_f32 v229, v164, v165
	v_add_co_u32_e32 v164, vcc, s16, v148
	v_add_f32_e32 v157, 1.0, v157
	s_nop 0
	v_addc_co_u32_e32 v165, vcc, 0, v149, vcc
	v_rcp_f32_e32 v162, v157
	v_mul_f32_e32 v157, 0xbfb8aa3b, v75
	v_exp_f32_e32 v157, v157
	s_mov_b64 s[16:17], 0x58000
	v_add_f32_e32 v157, 1.0, v157
	v_rcp_f32_e32 v163, v157
	v_mul_f32_e32 v157, 0xbfb8aa3b, v76
	v_exp_f32_e32 v157, v157
	v_pk_mul_f32 v[162:163], v[74:75], v[162:163]
	s_nop 0
	v_cvt_pk_bf16_f32 v230, v162, v163
	v_add_f32_e32 v157, 1.0, v157
	v_rcp_f32_e32 v164, v157
	v_mul_f32_e32 v157, 0xbfb8aa3b, v77
	v_exp_f32_e32 v157, v157
	s_nop 0
	v_add_f32_e32 v157, 1.0, v157
	v_rcp_f32_e32 v165, v157
	v_mul_f32_e32 v157, 0xbfb8aa3b, v70
	v_exp_f32_e32 v157, v157
	v_pk_mul_f32 v[164:165], v[76:77], v[164:165]
	s_nop 0
	v_cvt_pk_bf16_f32 v231, v164, v165
	v_add_f32_e32 v157, 1.0, v157
	s_nop 1
	v_permlane16_swap_b32_e32 v228, v230
	v_permlane16_swap_b32_e32 v229, v231
	v_lshl_add_u64 v[214:215], v[160:161], 0, v[226:227]
	global_store_dwordx4 v[214:215], v[228:231], off
	v_rcp_f32_e32 v162, v157
	v_mul_f32_e32 v157, 0xbfb8aa3b, v71
	v_exp_f32_e32 v157, v157
	v_lshl_add_u64 v[160:161], v[148:149], 0, s[16:17]
	s_mov_b32 s16, 0x58000
	v_add_co_u32_e32 v148, vcc, s16, v148
	v_add_f32_e32 v157, 1.0, v157
	v_rcp_f32_e32 v163, v157
	v_mul_f32_e32 v157, 0xbfb8aa3b, v72
	v_exp_f32_e32 v157, v157
	v_addc_co_u32_e32 v149, vcc, 0, v149, vcc
	v_pk_mul_f32 v[162:163], v[70:71], v[162:163]
	v_add_f32_e32 v157, 1.0, v157
	v_rcp_f32_e32 v164, v157
	v_mul_f32_e32 v157, 0xbfb8aa3b, v73
	v_exp_f32_e32 v157, v157
	v_cvt_pk_bf16_f32 v232, v162, v163
	v_add_f32_e32 v157, 1.0, v157
	v_rcp_f32_e32 v165, v157
	v_mul_f32_e32 v157, 0xbfb8aa3b, v68
	v_exp_f32_e32 v157, v157
	v_pk_mul_f32 v[164:165], v[72:73], v[164:165]
	s_nop 0
	v_cvt_pk_bf16_f32 v233, v164, v165
	v_add_f32_e32 v157, 1.0, v157
	v_mul_f32_e32 v148, 0xbfb8aa3b, v66
	v_mul_f32_e32 v149, 0xbfb8aa3b, v67
	v_rcp_f32_e32 v162, v157
	v_mul_f32_e32 v157, 0xbfb8aa3b, v69
	v_exp_f32_e32 v148, v148
	v_exp_f32_e32 v149, v149
	v_exp_f32_e32 v157, v157
	v_add_f32_e32 v148, 1.0, v148
	v_add_f32_e32 v149, 1.0, v149
	v_add_f32_e32 v157, 1.0, v157
	v_rcp_f32_e32 v148, v148
	v_rcp_f32_e32 v149, v149
	v_rcp_f32_e32 v163, v157
	v_pk_mul_f32 v[148:149], v[66:67], v[148:149]
	v_pk_mul_f32 v[162:163], v[68:69], v[162:163]
	v_cvt_pk_bf16_f32 v234, v148, v149
	v_cvt_pk_bf16_f32 v235, v162, v163
	s_nop 1
	v_permlane16_swap_b32_e32 v232, v234
	v_permlane16_swap_b32_e32 v233, v235
	v_lshl_add_u64 v[216:217], v[160:161], 0, v[226:227]
	global_store_dwordx4 v[216:217], v[232:235], off

.LBB0_397:
	v_xor_b32_e32 v157, 4, v156
	v_xor_b32_e32 v149, 8, v156
	v_xor_b32_e32 v148, 16, v156
	s_andn2_b64 vcc, exec, s[60:61]
	v_xor_b32_e32 v156, 32, v156
	s_cbranch_vccnz .LBB0_405
	s_ashr_i32 s60, s41, 1
	s_ashr_i32 s61, s60, 31
	s_lshl_b64 s[16:17], s[60:61], 25
	s_add_u32 s16, s50, s16
	s_addc_u32 s17, s51, s17
	s_cmp_lt_u32 s41, 2
	s_cselect_b64 vcc, -1, 0
	s_and_b32 s26, s55, 0x160
	v_mov_b32_e32 v159, 0x3e38aa3b
	v_add_u32_e32 v162, s26, v138
	v_cndmask_b32_e32 v160, 1.0, v159, vcc
	v_ashrrev_i32_e32 v163, 31, v162
	v_lshl_add_u64 v[162:163], v[162:163], 1, s[16:17]
	v_lshlrev_b64 v[164:165], 10, v[136:137]
	v_pk_mul_f32 v[128:129], v[160:161], v[128:129] op_sel_hi:[0,1]
	v_pk_mul_f32 v[126:127], v[160:161], v[126:127] op_sel_hi:[0,1]
	v_lshl_add_u64 v[162:163], v[162:163], 0, v[164:165]
	v_cvt_pk_bf16_f32 v236, v126, v127
	v_cvt_pk_bf16_f32 v237, v128, v129
	v_pk_mul_f32 v[124:125], v[160:161], v[124:125] op_sel_hi:[0,1]
	v_pk_mul_f32 v[122:123], v[160:161], v[122:123] op_sel_hi:[0,1]
	v_cvt_pk_bf16_f32 v238, v122, v123
	v_cvt_pk_bf16_f32 v239, v124, v125
	s_mov_b64 s[16:17], 0x4000
	s_nop 1
	v_permlane16_swap_b32_e32 v236, v238
	v_permlane16_swap_b32_e32 v237, v239
	v_lshl_add_u64 v[218:219], v[162:163], 0, v[226:227]
	global_store_dwordx4 v[218:219], v[236:239], off
	v_lshl_add_u64 v[164:165], v[162:163], 0, s[16:17]
	s_movk_i32 s16, 0x4000
	v_pk_mul_f32 v[120:121], v[160:161], v[120:121] op_sel_hi:[0,1]
	v_pk_mul_f32 v[118:119], v[160:161], v[118:119] op_sel_hi:[0,1]
	v_add_co_u32_e32 v170, vcc, s16, v162
	v_cvt_pk_bf16_f32 v240, v118, v119
	v_cvt_pk_bf16_f32 v241, v120, v121
	v_addc_co_u32_e32 v171, vcc, 0, v163, vcc
	v_pk_mul_f32 v[116:117], v[160:161], v[116:117] op_sel_hi:[0,1]
	v_pk_mul_f32 v[114:115], v[160:161], v[114:115] op_sel_hi:[0,1]
	v_cvt_pk_bf16_f32 v242, v114, v115
	v_cvt_pk_bf16_f32 v243, v116, v117
	s_mov_b64 s[16:17], 0x8000
	s_nop 1
	v_permlane16_swap_b32_e32 v240, v242
	v_permlane16_swap_b32_e32 v241, v243
	v_lshl_add_u64 v[214:215], v[164:165], 0, v[226:227]
	global_store_dwordx4 v[214:215], v[240:243], off
	v_lshl_add_u64 v[164:165], v[162:163], 0, s[16:17]
	s_mov_b32 s16, 0x8000
	v_pk_mul_f32 v[112:113], v[160:161], v[112:113] op_sel_hi:[0,1]
	v_pk_mul_f32 v[110:111], v[160:161], v[110:111] op_sel_hi:[0,1]
	v_add_co_u32_e32 v170, vcc, s16, v162
	v_cvt_pk_bf16_f32 v244, v110, v111
	v_cvt_pk_bf16_f32 v245, v112, v113
	v_addc_co_u32_e32 v171, vcc, 0, v163, vcc
	v_pk_mul_f32 v[108:109], v[160:161], v[108:109] op_sel_hi:[0,1]
	v_pk_mul_f32 v[106:107], v[160:161], v[106:107] op_sel_hi:[0,1]
	v_cvt_pk_bf16_f32 v246, v106, v107
	v_cvt_pk_bf16_f32 v247, v108, v109
	s_mov_b64 s[16:17], 0xc000
	s_nop 1
	v_permlane16_swap_b32_e32 v244, v246
	v_permlane16_swap_b32_e32 v245, v247
	v_lshl_add_u64 v[216:217], v[164:165], 0, v[226:227]
	global_store_dwordx4 v[216:217], v[244:247], off
	v_lshl_add_u64 v[164:165], v[162:163], 0, s[16:17]
	s_mov_b32 s16, 0xc000
	v_pk_mul_f32 v[104:105], v[160:161], v[104:105] op_sel_hi:[0,1]
	v_pk_mul_f32 v[102:103], v[160:161], v[102:103] op_sel_hi:[0,1]
	v_add_co_u32_e32 v170, vcc, s16, v162
	v_cvt_pk_bf16_f32 v248, v102, v103
	v_cvt_pk_bf16_f32 v249, v104, v105
	v_addc_co_u32_e32 v171, vcc, 0, v163, vcc
	v_pk_mul_f32 v[100:101], v[160:161], v[100:101] op_sel_hi:[0,1]
	v_pk_mul_f32 v[98:99], v[160:161], v[98:99] op_sel_hi:[0,1]
	s_mov_b32 s16, 0x20000
	v_cvt_pk_bf16_f32 v250, v98, v99
	v_cvt_pk_bf16_f32 v251, v100, v101
	v_pk_mul_f32 v[96:97], v[160:161], v[96:97] op_sel_hi:[0,1]
	v_pk_mul_f32 v[94:95], v[160:161], v[94:95] op_sel_hi:[0,1]
	v_add_co_u32_e32 v170, vcc, s16, v162
	s_nop 1
	v_permlane16_swap_b32_e32 v248, v250
	v_permlane16_swap_b32_e32 v249, v251
	v_lshl_add_u64 v[218:219], v[164:165], 0, v[226:227]
	global_store_dwordx4 v[218:219], v[248:251], off
	v_cvt_pk_bf16_f32 v228, v94, v95
	v_cvt_pk_bf16_f32 v229, v96, v97
	v_addc_co_u32_e32 v171, vcc, 0, v163, vcc
	v_pk_mul_f32 v[92:93], v[160:161], v[92:93] op_sel_hi:[0,1]
	v_pk_mul_f32 v[90:91], v[160:161], v[90:91] op_sel_hi:[0,1]
	v_lshl_add_u64 v[164:165], v[162:163], 0, s[46:47]
	v_cvt_pk_bf16_f32 v230, v90, v91
	v_cvt_pk_bf16_f32 v231, v92, v93
	s_mov_b64 s[16:17], 0x24000
	s_nop 1
	v_permlane16_swap_b32_e32 v228, v230
	v_permlane16_swap_b32_e32 v229, v231
	v_lshl_add_u64 v[214:215], v[164:165], 0, v[226:227]
	global_store_dwordx4 v[214:215], v[228:231], off
	v_lshl_add_u64 v[164:165], v[162:163], 0, s[16:17]
	s_mov_b32 s16, 0x24000
	v_pk_mul_f32 v[88:89], v[160:161], v[88:89] op_sel_hi:[0,1]
	v_pk_mul_f32 v[86:87], v[160:161], v[86:87] op_sel_hi:[0,1]
	v_add_co_u32_e32 v170, vcc, s16, v162
	v_cvt_pk_bf16_f32 v232, v86, v87
	v_cvt_pk_bf16_f32 v233, v88, v89
	v_addc_co_u32_e32 v171, vcc, 0, v163, vcc
	v_pk_mul_f32 v[84:85], v[160:161], v[84:85] op_sel_hi:[0,1]
	v_pk_mul_f32 v[82:83], v[160:161], v[82:83] op_sel_hi:[0,1]
	v_cvt_pk_bf16_f32 v234, v82, v83
	v_cvt_pk_bf16_f32 v235, v84, v85
	s_mov_b64 s[16:17], 0x28000
	s_nop 1
	v_permlane16_swap_b32_e32 v232, v234
	v_permlane16_swap_b32_e32 v233, v235
	v_lshl_add_u64 v[216:217], v[164:165], 0, v[226:227]
	global_store_dwordx4 v[216:217], v[232:235], off
	v_lshl_add_u64 v[164:165], v[162:163], 0, s[16:17]
	s_mov_b32 s16, 0x28000
	v_pk_mul_f32 v[80:81], v[160:161], v[80:81] op_sel_hi:[0,1]
	v_pk_mul_f32 v[78:79], v[160:161], v[78:79] op_sel_hi:[0,1]
	v_add_co_u32_e32 v170, vcc, s16, v162
	v_cvt_pk_bf16_f32 v236, v78, v79
	v_cvt_pk_bf16_f32 v237, v80, v81
	v_addc_co_u32_e32 v171, vcc, 0, v163, vcc
	v_pk_mul_f32 v[76:77], v[160:161], v[76:77] op_sel_hi:[0,1]
	v_pk_mul_f32 v[74:75], v[160:161], v[74:75] op_sel_hi:[0,1]
	v_cvt_pk_bf16_f32 v238, v74, v75
	v_cvt_pk_bf16_f32 v239, v76, v77
	s_mov_b64 s[16:17], 0x2c000
	s_nop 1
	v_permlane16_swap_b32_e32 v236, v238
	v_permlane16_swap_b32_e32 v237, v239
	v_lshl_add_u64 v[218:219], v[164:165], 0, v[226:227]
	global_store_dwordx4 v[218:219], v[236:239], off
	v_lshl_add_u64 v[164:165], v[162:163], 0, s[16:17]
	s_mov_b32 s16, 0x2c000
	v_pk_mul_f32 v[72:73], v[160:161], v[72:73] op_sel_hi:[0,1]
	v_pk_mul_f32 v[70:71], v[160:161], v[70:71] op_sel_hi:[0,1]
	v_add_co_u32_e32 v162, vcc, s16, v162
	v_pk_mul_f32 v[68:69], v[160:161], v[68:69] op_sel_hi:[0,1]
	v_pk_mul_f32 v[66:67], v[160:161], v[66:67] op_sel_hi:[0,1]
	v_cvt_pk_bf16_f32 v240, v70, v71
	v_cvt_pk_bf16_f32 v241, v72, v73
	v_addc_co_u32_e32 v163, vcc, 0, v163, vcc
	v_cvt_pk_bf16_f32 v242, v66, v67
	v_cvt_pk_bf16_f32 v243, v68, v69
	s_cmp_gt_i32 s60, 1
	s_nop 1
	v_permlane16_swap_b32_e32 v240, v242
	v_permlane16_swap_b32_e32 v241, v243
	v_lshl_add_u64 v[214:215], v[164:165], 0, v[226:227]
	global_store_dwordx4 v[214:215], v[240:243], off
	s_cbranch_scc1 .LBB0_405
	v_mul_f32_e32 v127, v127, v127
	v_mul_f32_e32 v123, v123, v123
	v_mul_f32_e32 v119, v119, v119
	v_mul_f32_e32 v115, v115, v115
	v_fmac_f32_e32 v127, v126, v126
	v_mul_f32_e32 v126, v129, v129
	v_fmac_f32_e32 v123, v122, v122
	v_mul_f32_e32 v122, v125, v125
	v_fmac_f32_e32 v119, v118, v118
	v_mul_f32_e32 v118, v121, v121
	v_fmac_f32_e32 v115, v114, v114
	v_mul_f32_e32 v114, v117, v117
	v_mul_f32_e32 v111, v111, v111
	v_mul_f32_e32 v107, v107, v107
	v_mul_f32_e32 v103, v103, v103
	v_mul_f32_e32 v99, v99, v99
	v_fmac_f32_e32 v126, v128, v128
	v_fmac_f32_e32 v122, v124, v124
	v_fmac_f32_e32 v118, v120, v120
	v_fmac_f32_e32 v114, v116, v116
	v_fmac_f32_e32 v111, v110, v110
	v_mul_f32_e32 v110, v113, v113
	v_fmac_f32_e32 v107, v106, v106
	v_mul_f32_e32 v106, v109, v109
	v_fmac_f32_e32 v103, v102, v102
	v_mul_f32_e32 v102, v105, v105
	v_fmac_f32_e32 v99, v98, v98
	v_mul_f32_e32 v98, v101, v101
	v_mul_f32_e32 v95, v95, v95
	v_mul_f32_e32 v91, v91, v91
	v_mul_f32_e32 v87, v87, v87
	v_mul_f32_e32 v83, v83, v83
	v_add_f32_e32 v126, v127, v126
	v_add_f32_e32 v122, v123, v122
	v_add_f32_e32 v118, v119, v118
	v_add_f32_e32 v114, v115, v114
	v_fmac_f32_e32 v110, v112, v112
	v_fmac_f32_e32 v106, v108, v108
	v_fmac_f32_e32 v102, v104, v104
	v_fmac_f32_e32 v98, v100, v100
	v_fmac_f32_e32 v95, v94, v94
	v_mul_f32_e32 v94, v97, v97
	v_fmac_f32_e32 v91, v90, v90
	v_mul_f32_e32 v90, v93, v93
	v_fmac_f32_e32 v87, v86, v86
	v_mul_f32_e32 v86, v89, v89
	v_fmac_f32_e32 v83, v82, v82
	v_mul_f32_e32 v82, v85, v85
	v_mul_f32_e32 v79, v79, v79
	v_mul_f32_e32 v75, v75, v75
	v_mul_f32_e32 v71, v71, v71
	v_mul_f32_e32 v67, v67, v67
	v_add_f32_e32 v122, v126, v122
	v_add_f32_e32 v114, v118, v114
	v_add_f32_e32 v110, v111, v110
	v_add_f32_e32 v106, v107, v106
	v_add_f32_e32 v102, v103, v102
	v_add_f32_e32 v98, v99, v98
	v_fmac_f32_e32 v94, v96, v96
	v_fmac_f32_e32 v90, v92, v92
	v_fmac_f32_e32 v86, v88, v88
	v_fmac_f32_e32 v82, v84, v84
	v_fmac_f32_e32 v79, v78, v78
	v_mul_f32_e32 v78, v81, v81
	v_fmac_f32_e32 v75, v74, v74
	v_mul_f32_e32 v74, v77, v77
	v_fmac_f32_e32 v71, v70, v70
	v_mul_f32_e32 v70, v73, v73
	v_fmac_f32_e32 v67, v66, v66
	v_mul_f32_e32 v66, v69, v69
	ds_bpermute_b32 v123, v155, v122
	ds_bpermute_b32 v115, v155, v114
	v_add_f32_e32 v106, v110, v106
	v_add_f32_e32 v98, v102, v98
	v_add_f32_e32 v94, v95, v94
	v_add_f32_e32 v90, v91, v90
	v_add_f32_e32 v86, v87, v86
	v_add_f32_e32 v82, v83, v82
	v_fmac_f32_e32 v78, v80, v80
	v_fmac_f32_e32 v74, v76, v76
	v_fmac_f32_e32 v70, v72, v72
	v_fmac_f32_e32 v66, v68, v68
	ds_bpermute_b32 v107, v155, v106
	ds_bpermute_b32 v99, v155, v98
	v_add_f32_e32 v90, v94, v90
	v_add_f32_e32 v82, v86, v82
	v_add_f32_e32 v78, v79, v78
	v_add_f32_e32 v74, v75, v74
	v_add_f32_e32 v70, v71, v70
	v_add_f32_e32 v66, v67, v66
	ds_bpermute_b32 v91, v155, v90
	ds_bpermute_b32 v83, v155, v82
	v_add_f32_e32 v74, v78, v74
	v_add_f32_e32 v66, v70, v66
	ds_bpermute_b32 v75, v155, v74
	ds_bpermute_b32 v67, v155, v66
	s_waitcnt lgkmcnt(0)
	v_add_f32_e32 v116, v122, v123
	v_add_f32_e32 v114, v114, v115
	ds_bpermute_b32 v117, v154, v116
	ds_bpermute_b32 v115, v154, v114
	v_add_f32_e32 v102, v106, v107
	v_add_f32_e32 v98, v98, v99
	ds_bpermute_b32 v103, v154, v102
	ds_bpermute_b32 v99, v154, v98
	v_add_f32_e32 v90, v90, v91
	v_add_f32_e32 v68, v82, v83
	ds_bpermute_b32 v91, v154, v90
	ds_bpermute_b32 v69, v154, v68
	v_add_f32_e32 v70, v74, v75
	v_add_f32_e32 v66, v66, v67
	ds_bpermute_b32 v71, v154, v70
	ds_bpermute_b32 v67, v154, v66
	s_waitcnt lgkmcnt(0)
	v_add_f32_e32 v100, v116, v117
	v_add_f32_e32 v101, v114, v115
	v_max3_f32 v92, v100, 0, v101
	v_add_f32_e32 v93, v102, v103
	v_add_f32_e32 v94, v98, v99
	v_max3_f32 v92, v92, v93, v94
	v_add_f32_e32 v72, v90, v91
	v_add_f32_e32 v68, v68, v69
	v_max3_f32 v68, v92, v72, v68
	v_add_f32_e32 v69, v70, v71
	v_add_f32_e32 v66, v66, v67
	v_max3_f32 v66, v68, v69, v66
	ds_bpermute_b32 v67, v157, v66
	s_waitcnt lgkmcnt(0)
	v_max_f32_e32 v67, v67, v67
	v_max_f32_e32 v66, v66, v67
	ds_bpermute_b32 v67, v149, v66
	s_waitcnt lgkmcnt(0)
	v_max_f32_e32 v67, v67, v67
	v_max_f32_e32 v66, v66, v67
	ds_bpermute_b32 v67, v148, v66
	s_waitcnt lgkmcnt(0)
	v_max_f32_e32 v67, v67, v67
	v_max_f32_e32 v66, v66, v67
	ds_bpermute_b32 v67, v156, v66
	s_and_saveexec_b64 s[62:63], s[4:5]
	s_cbranch_execz .LBB0_404
	s_waitcnt lgkmcnt(0)
	v_max_f32_e32 v67, v67, v67
	v_max_f32_e32 v66, v66, v66
	s_mov_b64 s[64:65], exec
	v_max_f32_e32 v66, v66, v67
	s_mov_b32 s16, 0

.LBB0_412:
	s_andn2_b64 vcc, exec, s[62:63]
	s_cbranch_vccnz .LBB0_414
	s_waitcnt lgkmcnt(0)
	v_lshlrev_b64 v[66:67], 6, v[136:137]
	v_lshl_add_u64 v[68:69], v[144:145], 0, v[66:67]
	v_lshl_add_u64 v[72:73], v[142:143], 0, v[66:67]
	global_load_dwordx4 v[68:71], v[68:69], off
	s_mov_b64 s[16:17], 0x400
	global_load_dwordx4 v[72:75], v[72:73], off
	s_waitcnt vmcnt(0)
	v_pk_mul_f32 v[76:77], v[60:61], v[74:75]
	v_pk_mul_f32 v[78:79], v[58:59], v[72:73]
	v_pk_mul_f32 v[74:75], v[64:65], v[74:75]
	v_pk_mul_f32 v[72:73], v[62:63], v[72:73]
	v_pk_fma_f32 v[76:77], v[64:65], v[70:71], v[76:77] neg_lo:[0,0,1] neg_hi:[0,0,1]
	v_pk_fma_f32 v[78:79], v[62:63], v[68:69], v[78:79] neg_lo:[0,0,1] neg_hi:[0,0,1]
	v_pk_fma_f32 v[70:71], v[60:61], v[70:71], v[74:75]
	v_pk_fma_f32 v[68:69], v[58:59], v[68:69], v[72:73]
	v_lshl_add_u64 v[72:73], v[140:141], 0, v[66:67]
	v_cvt_pk_bf16_f32 v244, v78, v79
	v_cvt_pk_bf16_f32 v245, v76, v77
	v_cvt_pk_bf16_f32 v246, v68, v69
	v_cvt_pk_bf16_f32 v247, v70, v71
	v_lshl_add_u64 v[76:77], v[66:67], 0, s[16:17]
	s_nop 1
	v_permlane16_swap_b32_e32 v244, v246
	v_permlane16_swap_b32_e32 v245, v247
	v_lshl_add_u64 v[216:217], v[72:73], 0, v[226:227]
	global_store_dwordx4 v[216:217], v[244:247], off
	v_lshl_add_u64 v[68:69], v[144:145], 0, v[76:77]
	v_lshl_add_u64 v[72:73], v[142:143], 0, v[76:77]
	global_load_dwordx4 v[68:71], v[68:69], off
	s_mov_b64 s[16:17], 0xc00
	global_load_dwordx4 v[72:75], v[72:73], off
	s_waitcnt vmcnt(0)
	v_pk_mul_f32 v[78:79], v[52:53], v[74:75]
	v_pk_mul_f32 v[80:81], v[50:51], v[72:73]
	v_pk_mul_f32 v[74:75], v[56:57], v[74:75]
	v_pk_mul_f32 v[72:73], v[54:55], v[72:73]
	v_pk_fma_f32 v[78:79], v[56:57], v[70:71], v[78:79] neg_lo:[0,0,1] neg_hi:[0,0,1]
	v_pk_fma_f32 v[80:81], v[54:55], v[68:69], v[80:81] neg_lo:[0,0,1] neg_hi:[0,0,1]
	v_pk_fma_f32 v[70:71], v[52:53], v[70:71], v[74:75]
	v_pk_fma_f32 v[68:69], v[50:51], v[68:69], v[72:73]
	v_lshl_add_u64 v[72:73], v[140:141], 0, v[76:77]
	v_cvt_pk_bf16_f32 v248, v80, v81
	v_cvt_pk_bf16_f32 v249, v78, v79
	v_cvt_pk_bf16_f32 v250, v68, v69
	v_cvt_pk_bf16_f32 v251, v70, v71
	s_nop 1
	v_permlane16_swap_b32_e32 v248, v250
	v_permlane16_swap_b32_e32 v249, v251
	v_lshl_add_u64 v[218:219], v[72:73], 0, v[226:227]
	global_store_dwordx4 v[218:219], v[248:251], off
	v_lshl_add_u64 v[76:77], v[66:67], 0, s[36:37]
	v_lshl_add_u64 v[68:69], v[144:145], 0, v[76:77]
	v_lshl_add_u64 v[72:73], v[142:143], 0, v[76:77]
	global_load_dwordx4 v[68:71], v[68:69], off
	s_nop 0
	global_load_dwordx4 v[72:75], v[72:73], off
	s_waitcnt vmcnt(0)
	v_pk_mul_f32 v[78:79], v[44:45], v[74:75]
	v_pk_mul_f32 v[80:81], v[42:43], v[72:73]
	v_pk_mul_f32 v[74:75], v[48:49], v[74:75]
	v_pk_mul_f32 v[72:73], v[46:47], v[72:73]
	v_pk_fma_f32 v[78:79], v[48:49], v[70:71], v[78:79] neg_lo:[0,0,1] neg_hi:[0,0,1]
	v_pk_fma_f32 v[80:81], v[46:47], v[68:69], v[80:81] neg_lo:[0,0,1] neg_hi:[0,0,1]
	v_pk_fma_f32 v[70:71], v[44:45], v[70:71], v[74:75]
	v_pk_fma_f32 v[68:69], v[42:43], v[68:69], v[72:73]
	v_lshl_add_u64 v[72:73], v[140:141], 0, v[76:77]
	v_cvt_pk_bf16_f32 v228, v80, v81
	v_cvt_pk_bf16_f32 v229, v78, v79
	v_cvt_pk_bf16_f32 v230, v68, v69
	v_cvt_pk_bf16_f32 v231, v70, v71
	v_lshl_add_u64 v[76:77], v[66:67], 0, s[16:17]
	s_nop 1
	v_permlane16_swap_b32_e32 v228, v230
	v_permlane16_swap_b32_e32 v229, v231
	v_lshl_add_u64 v[214:215], v[72:73], 0, v[226:227]
	global_store_dwordx4 v[214:215], v[228:231], off
	v_lshl_add_u64 v[68:69], v[144:145], 0, v[76:77]
	v_lshl_add_u64 v[72:73], v[142:143], 0, v[76:77]
	global_load_dwordx4 v[68:71], v[68:69], off
	s_mov_b64 s[16:17], 0x2400
	global_load_dwordx4 v[72:75], v[72:73], off
	s_waitcnt vmcnt(0)
	v_pk_mul_f32 v[78:79], v[36:37], v[74:75]
	v_pk_mul_f32 v[80:81], v[34:35], v[72:73]
	v_pk_mul_f32 v[74:75], v[40:41], v[74:75]
	v_pk_mul_f32 v[72:73], v[38:39], v[72:73]
	v_pk_fma_f32 v[78:79], v[40:41], v[70:71], v[78:79] neg_lo:[0,0,1] neg_hi:[0,0,1]
	v_pk_fma_f32 v[80:81], v[38:39], v[68:69], v[80:81] neg_lo:[0,0,1] neg_hi:[0,0,1]
	v_pk_fma_f32 v[70:71], v[36:37], v[70:71], v[74:75]
	v_pk_fma_f32 v[68:69], v[34:35], v[68:69], v[72:73]
	v_lshl_add_u64 v[72:73], v[140:141], 0, v[76:77]
	v_cvt_pk_bf16_f32 v232, v80, v81
	v_cvt_pk_bf16_f32 v233, v78, v79
	v_cvt_pk_bf16_f32 v234, v68, v69
	v_cvt_pk_bf16_f32 v235, v70, v71
	s_nop 1
	v_permlane16_swap_b32_e32 v232, v234
	v_permlane16_swap_b32_e32 v233, v235
	v_lshl_add_u64 v[216:217], v[72:73], 0, v[226:227]
	global_store_dwordx4 v[216:217], v[232:235], off
	v_lshl_add_u64 v[76:77], v[66:67], 0, s[68:69]
	v_lshl_add_u64 v[68:69], v[144:145], 0, v[76:77]
	v_lshl_add_u64 v[72:73], v[142:143], 0, v[76:77]
	global_load_dwordx4 v[68:71], v[68:69], off
	s_nop 0
	global_load_dwordx4 v[72:75], v[72:73], off
	s_waitcnt vmcnt(0)
	v_pk_mul_f32 v[78:79], v[28:29], v[74:75]
	v_pk_mul_f32 v[80:81], v[26:27], v[72:73]
	v_pk_mul_f32 v[74:75], v[32:33], v[74:75]
	v_pk_mul_f32 v[72:73], v[30:31], v[72:73]
	v_pk_fma_f32 v[78:79], v[32:33], v[70:71], v[78:79] neg_lo:[0,0,1] neg_hi:[0,0,1]
	v_pk_fma_f32 v[80:81], v[30:31], v[68:69], v[80:81] neg_lo:[0,0,1] neg_hi:[0,0,1]
	v_pk_fma_f32 v[70:71], v[28:29], v[70:71], v[74:75]
	v_pk_fma_f32 v[68:69], v[26:27], v[68:69], v[72:73]
	v_lshl_add_u64 v[72:73], v[140:141], 0, v[76:77]
	v_cvt_pk_bf16_f32 v236, v80, v81
	v_cvt_pk_bf16_f32 v237, v78, v79
	v_cvt_pk_bf16_f32 v238, v68, v69
	v_cvt_pk_bf16_f32 v239, v70, v71
	v_lshl_add_u64 v[76:77], v[66:67], 0, s[16:17]
	s_nop 1
	v_permlane16_swap_b32_e32 v236, v238
	v_permlane16_swap_b32_e32 v237, v239
	v_lshl_add_u64 v[218:219], v[72:73], 0, v[226:227]
	global_store_dwordx4 v[218:219], v[236:239], off
	v_lshl_add_u64 v[68:69], v[144:145], 0, v[76:77]
	v_lshl_add_u64 v[72:73], v[142:143], 0, v[76:77]
	global_load_dwordx4 v[68:71], v[68:69], off
	s_mov_b64 s[16:17], 0x2800
	global_load_dwordx4 v[72:75], v[72:73], off
	s_waitcnt vmcnt(0)
	v_pk_mul_f32 v[78:79], v[20:21], v[74:75]
	v_pk_mul_f32 v[80:81], v[18:19], v[72:73]
	v_pk_mul_f32 v[74:75], v[24:25], v[74:75]
	v_pk_mul_f32 v[72:73], v[22:23], v[72:73]
	v_pk_fma_f32 v[78:79], v[24:25], v[70:71], v[78:79] neg_lo:[0,0,1] neg_hi:[0,0,1]
	v_pk_fma_f32 v[80:81], v[22:23], v[68:69], v[80:81] neg_lo:[0,0,1] neg_hi:[0,0,1]
	v_pk_fma_f32 v[70:71], v[20:21], v[70:71], v[74:75]
	v_pk_fma_f32 v[68:69], v[18:19], v[68:69], v[72:73]
	v_lshl_add_u64 v[72:73], v[140:141], 0, v[76:77]
	v_cvt_pk_bf16_f32 v240, v80, v81
	v_cvt_pk_bf16_f32 v241, v78, v79
	v_cvt_pk_bf16_f32 v242, v68, v69
	v_cvt_pk_bf16_f32 v243, v70, v71
	s_nop 1
	v_permlane16_swap_b32_e32 v240, v242
	v_permlane16_swap_b32_e32 v241, v243
	v_lshl_add_u64 v[214:215], v[72:73], 0, v[226:227]
	global_store_dwordx4 v[214:215], v[240:243], off
	v_lshl_add_u64 v[76:77], v[66:67], 0, s[16:17]
	v_lshl_add_u64 v[68:69], v[144:145], 0, v[76:77]
	v_lshl_add_u64 v[72:73], v[142:143], 0, v[76:77]
	global_load_dwordx4 v[68:71], v[68:69], off
	s_mov_b64 s[16:17], 0x2c00
	global_load_dwordx4 v[72:75], v[72:73], off
	s_waitcnt vmcnt(0)
	v_pk_mul_f32 v[78:79], v[10:11], v[74:75]
	v_pk_mul_f32 v[80:81], v[8:9], v[72:73]
	v_pk_fma_f32 v[78:79], v[16:17], v[70:71], v[78:79] neg_lo:[0,0,1] neg_hi:[0,0,1]
	v_pk_fma_f32 v[80:81], v[14:15], v[68:69], v[80:81] neg_lo:[0,0,1] neg_hi:[0,0,1]
	v_pk_mul_f32 v[74:75], v[16:17], v[74:75]
	v_pk_mul_f32 v[72:73], v[14:15], v[72:73]
	v_pk_fma_f32 v[70:71], v[10:11], v[70:71], v[74:75]
	v_pk_fma_f32 v[68:69], v[8:9], v[68:69], v[72:73]
	v_lshl_add_u64 v[72:73], v[140:141], 0, v[76:77]
	v_cvt_pk_bf16_f32 v244, v80, v81
	v_cvt_pk_bf16_f32 v245, v78, v79
	v_cvt_pk_bf16_f32 v246, v68, v69
	v_cvt_pk_bf16_f32 v247, v70, v71
	v_lshl_add_u64 v[74:75], v[66:67], 0, s[16:17]
	s_nop 1
	v_permlane16_swap_b32_e32 v244, v246
	v_permlane16_swap_b32_e32 v245, v247
	v_lshl_add_u64 v[216:217], v[72:73], 0, v[226:227]
	global_store_dwordx4 v[216:217], v[244:247], off
	v_lshl_add_u64 v[66:67], v[144:145], 0, v[74:75]
	v_lshl_add_u64 v[70:71], v[142:143], 0, v[74:75]
	global_load_dwordx4 v[66:69], v[66:67], off
	s_nop 0
	global_load_dwordx4 v[70:73], v[70:71], off
	s_waitcnt vmcnt(0)
	v_pk_mul_f32 v[76:77], v[2:3], v[72:73]
	v_pk_mul_f32 v[78:79], v[0:1], v[70:71]
	v_pk_mul_f32 v[72:73], v[6:7], v[72:73]
	v_pk_mul_f32 v[70:71], v[4:5], v[70:71]
	v_pk_fma_f32 v[76:77], v[6:7], v[68:69], v[76:77] neg_lo:[0,0,1] neg_hi:[0,0,1]
	v_pk_fma_f32 v[78:79], v[4:5], v[66:67], v[78:79] neg_lo:[0,0,1] neg_hi:[0,0,1]
	v_pk_fma_f32 v[68:69], v[2:3], v[68:69], v[72:73]
	v_pk_fma_f32 v[66:67], v[0:1], v[66:67], v[70:71]
	v_lshl_add_u64 v[70:71], v[140:141], 0, v[74:75]
	v_cvt_pk_bf16_f32 v248, v78, v79
	v_cvt_pk_bf16_f32 v249, v76, v77
	v_cvt_pk_bf16_f32 v250, v66, v67
	v_cvt_pk_bf16_f32 v251, v68, v69
	s_nop 1
	v_permlane16_swap_b32_e32 v248, v250
	v_permlane16_swap_b32_e32 v249, v251
	v_lshl_add_u64 v[218:219], v[70:71], 0, v[226:227]
	global_store_dwordx4 v[218:219], v[248:251], off

.LBB0_415:
	s_andn2_b64 vcc, exec, s[62:63]
	s_cbranch_vccnz .LBB0_417
	v_add_u32_e32 v66, s53, v139
	s_waitcnt lgkmcnt(0)
	v_ashrrev_i32_e32 v67, 31, v66
	v_lshl_add_u64 v[66:67], v[66:67], 1, s[44:45]
	v_lshlrev_b64 v[68:69], 9, v[136:137]
	v_lshl_add_u64 v[66:67], v[66:67], 0, v[68:69]
	s_movk_i32 s16, 0x2000
	v_cvt_pk_bf16_f32 v228, v62, v63
	v_cvt_pk_bf16_f32 v229, v64, v65
	v_add_co_u32_e32 v72, vcc, s16, v66
	v_cvt_pk_bf16_f32 v230, v58, v59
	v_cvt_pk_bf16_f32 v231, v60, v61
	v_cvt_pk_bf16_f32 v232, v54, v55
	v_cvt_pk_bf16_f32 v233, v56, v57
	v_addc_co_u32_e32 v73, vcc, 0, v67, vcc
	s_nop 1
	v_permlane16_swap_b32_e32 v228, v230
	v_permlane16_swap_b32_e32 v229, v231
	v_lshl_add_u64 v[214:215], v[66:67], 0, v[226:227]
	global_store_dwordx4 v[214:215], v[228:231], off
	v_lshl_add_u64 v[68:69], v[66:67], 0, s[68:69]
	v_cvt_pk_bf16_f32 v234, v50, v51
	v_cvt_pk_bf16_f32 v235, v52, v53
	s_mov_b64 s[16:17], 0x4000
	s_nop 1
	v_permlane16_swap_b32_e32 v232, v234
	v_permlane16_swap_b32_e32 v233, v235
	v_lshl_add_u64 v[216:217], v[68:69], 0, v[226:227]
	global_store_dwordx4 v[216:217], v[232:235], off
	v_lshl_add_u64 v[68:69], v[66:67], 0, s[16:17]
	s_movk_i32 s16, 0x4000
	v_add_co_u32_e32 v72, vcc, s16, v66
	v_cvt_pk_bf16_f32 v236, v46, v47
	v_cvt_pk_bf16_f32 v237, v48, v49
	v_addc_co_u32_e32 v73, vcc, 0, v67, vcc
	v_cvt_pk_bf16_f32 v238, v42, v43
	v_cvt_pk_bf16_f32 v239, v44, v45
	s_mov_b64 s[16:17], 0x6000
	s_nop 1
	v_permlane16_swap_b32_e32 v236, v238
	v_permlane16_swap_b32_e32 v237, v239
	v_lshl_add_u64 v[218:219], v[68:69], 0, v[226:227]
	global_store_dwordx4 v[218:219], v[236:239], off
	v_lshl_add_u64 v[68:69], v[66:67], 0, s[16:17]
	s_movk_i32 s16, 0x6000
	v_add_co_u32_e32 v72, vcc, s16, v66
	v_cvt_pk_bf16_f32 v240, v38, v39
	v_cvt_pk_bf16_f32 v241, v40, v41
	v_addc_co_u32_e32 v73, vcc, 0, v67, vcc
	v_cvt_pk_bf16_f32 v242, v34, v35
	v_cvt_pk_bf16_f32 v243, v36, v37
	s_mov_b64 s[16:17], 0x10000
	s_nop 1
	v_permlane16_swap_b32_e32 v240, v242
	v_permlane16_swap_b32_e32 v241, v243
	v_lshl_add_u64 v[214:215], v[68:69], 0, v[226:227]
	global_store_dwordx4 v[214:215], v[240:243], off
	v_lshl_add_u64 v[68:69], v[66:67], 0, s[16:17]
	s_mov_b32 s16, 0x10000
	v_add_co_u32_e32 v72, vcc, s16, v66
	v_cvt_pk_bf16_f32 v244, v30, v31
	v_cvt_pk_bf16_f32 v245, v32, v33
	v_addc_co_u32_e32 v73, vcc, 0, v67, vcc
	v_cvt_pk_bf16_f32 v246, v26, v27
	v_cvt_pk_bf16_f32 v247, v28, v29
	s_mov_b64 s[16:17], 0x12000
	s_nop 1
	v_permlane16_swap_b32_e32 v244, v246
	v_permlane16_swap_b32_e32 v245, v247
	v_lshl_add_u64 v[216:217], v[68:69], 0, v[226:227]
	global_store_dwordx4 v[216:217], v[244:247], off
	v_lshl_add_u64 v[68:69], v[66:67], 0, s[16:17]
	s_mov_b32 s16, 0x12000
	v_add_co_u32_e32 v72, vcc, s16, v66
	v_cvt_pk_bf16_f32 v248, v22, v23
	v_cvt_pk_bf16_f32 v249, v24, v25
	v_addc_co_u32_e32 v73, vcc, 0, v67, vcc
	v_cvt_pk_bf16_f32 v250, v18, v19
	v_cvt_pk_bf16_f32 v251, v20, v21
	s_mov_b64 s[16:17], 0x14000
	s_nop 1
	v_permlane16_swap_b32_e32 v248, v250
	v_permlane16_swap_b32_e32 v249, v251
	v_lshl_add_u64 v[218:219], v[68:69], 0, v[226:227]
	global_store_dwordx4 v[218:219], v[248:251], off
	v_lshl_add_u64 v[68:69], v[66:67], 0, s[16:17]
	s_mov_b32 s16, 0x14000
	v_add_co_u32_e32 v72, vcc, s16, v66
	v_cvt_pk_bf16_f32 v228, v14, v15
	v_cvt_pk_bf16_f32 v229, v16, v17
	v_addc_co_u32_e32 v73, vcc, 0, v67, vcc
	v_cvt_pk_bf16_f32 v230, v8, v9
	v_cvt_pk_bf16_f32 v231, v10, v11
	s_mov_b64 s[16:17], 0x16000
	s_nop 1
	v_permlane16_swap_b32_e32 v228, v230
	v_permlane16_swap_b32_e32 v229, v231
	v_lshl_add_u64 v[214:215], v[68:69], 0, v[226:227]
	global_store_dwordx4 v[214:215], v[228:231], off
	v_lshl_add_u64 v[68:69], v[66:67], 0, s[16:17]
	v_add_co_u32_e32 v66, vcc, 0x16000, v66
	v_cvt_pk_bf16_f32 v232, v4, v5
	v_cvt_pk_bf16_f32 v233, v6, v7
	v_addc_co_u32_e32 v67, vcc, 0, v67, vcc
	v_cvt_pk_bf16_f32 v234, v0, v1
	v_cvt_pk_bf16_f32 v235, v2, v3
	s_nop 1
	v_permlane16_swap_b32_e32 v232, v234
	v_permlane16_swap_b32_e32 v233, v235
	v_lshl_add_u64 v[216:217], v[68:69], 0, v[226:227]
	global_store_dwordx4 v[216:217], v[232:235], off

.LBB0_418:
	s_andn2_b64 vcc, exec, s[62:63]
	s_cbranch_vccnz .LBB0_420
	s_and_b64 s[16:17], s[60:61], exec
	s_movk_i32 s16, 0xfa00
	s_cselect_b32 s16, s16, 0xfffff860
	s_add_i32 s16, s16, s53
	v_add_u32_e32 v66, s16, v138
	v_readlane_b32 s16, v253, 38
	s_waitcnt lgkmcnt(0)
	v_ashrrev_i32_e32 v67, 31, v66
	v_readlane_b32 s17, v253, 39
	v_lshlrev_b64 v[68:69], 11, v[136:137]
	v_mul_f32_e32 v70, 0xbfb8aa3b, v64
	v_lshl_add_u64 v[66:67], v[66:67], 1, s[16:17]
	v_lshl_add_u64 v[66:67], v[66:67], 0, v[68:69]
	v_mul_f32_e32 v68, 0xbfb8aa3b, v62
	v_mul_f32_e32 v69, 0xbfb8aa3b, v63
	v_mul_f32_e32 v71, 0xbfb8aa3b, v65
	v_exp_f32_e32 v68, v68
	v_exp_f32_e32 v69, v69
	v_exp_f32_e32 v70, v70
	v_exp_f32_e32 v71, v71
	v_add_f32_e32 v68, 1.0, v68
	v_add_f32_e32 v69, 1.0, v69
	v_add_f32_e32 v70, 1.0, v70
	v_add_f32_e32 v71, 1.0, v71
	v_rcp_f32_e32 v68, v68
	v_rcp_f32_e32 v69, v69
	v_rcp_f32_e32 v70, v70
	v_rcp_f32_e32 v71, v71
	v_mul_f32_e32 v72, 0xbfb8aa3b, v56
	v_pk_mul_f32 v[68:69], v[62:63], v[68:69]
	v_mul_f32_e32 v73, 0xbfb8aa3b, v57
	v_pk_mul_f32 v[70:71], v[64:65], v[70:71]
	v_cvt_pk_bf16_f32 v236, v68, v69
	v_cvt_pk_bf16_f32 v237, v70, v71
	v_mul_f32_e32 v68, 0xbfb8aa3b, v58
	v_mul_f32_e32 v69, 0xbfb8aa3b, v59
	v_mul_f32_e32 v70, 0xbfb8aa3b, v60
	v_mul_f32_e32 v71, 0xbfb8aa3b, v61
	v_exp_f32_e32 v68, v68
	v_exp_f32_e32 v69, v69
	v_exp_f32_e32 v70, v70
	v_exp_f32_e32 v71, v71
	v_add_f32_e32 v68, 1.0, v68
	v_add_f32_e32 v69, 1.0, v69
	v_add_f32_e32 v70, 1.0, v70
	v_add_f32_e32 v71, 1.0, v71
	v_rcp_f32_e32 v68, v68
	v_rcp_f32_e32 v69, v69
	v_rcp_f32_e32 v70, v70
	v_rcp_f32_e32 v71, v71
	v_exp_f32_e32 v72, v72
	v_pk_mul_f32 v[68:69], v[58:59], v[68:69]
	v_exp_f32_e32 v73, v73
	v_pk_mul_f32 v[70:71], v[60:61], v[70:71]
	v_cvt_pk_bf16_f32 v238, v68, v69
	v_cvt_pk_bf16_f32 v239, v70, v71
	v_mul_f32_e32 v70, 0xbfb8aa3b, v54
	v_mul_f32_e32 v71, 0xbfb8aa3b, v55
	v_exp_f32_e32 v70, v70
	v_exp_f32_e32 v71, v71
	v_add_f32_e32 v72, 1.0, v72
	v_add_f32_e32 v73, 1.0, v73
	v_add_f32_e32 v70, 1.0, v70
	v_add_f32_e32 v71, 1.0, v71
	v_rcp_f32_e32 v70, v70
	v_rcp_f32_e32 v71, v71
	v_rcp_f32_e32 v72, v72
	v_rcp_f32_e32 v73, v73
	s_mov_b64 s[16:17], 0x8000
	s_nop 1
	v_permlane16_swap_b32_e32 v236, v238
	v_permlane16_swap_b32_e32 v237, v239
	v_lshl_add_u64 v[218:219], v[66:67], 0, v[226:227]
	global_store_dwordx4 v[218:219], v[236:239], off
	v_lshl_add_u64 v[68:69], v[66:67], 0, s[16:17]
	v_pk_mul_f32 v[70:71], v[54:55], v[70:71]
	v_pk_mul_f32 v[72:73], v[56:57], v[72:73]
	s_mov_b32 s16, 0x8000
	v_cvt_pk_bf16_f32 v240, v70, v71
	v_cvt_pk_bf16_f32 v241, v72, v73
	v_add_co_u32_e32 v72, vcc, s16, v66
	s_mov_b64 s[16:17], 0x10000
	s_nop 0
	v_addc_co_u32_e32 v73, vcc, 0, v67, vcc
	v_mul_f32_e32 v70, 0xbfb8aa3b, v50
	v_mul_f32_e32 v71, 0xbfb8aa3b, v51
	v_mul_f32_e32 v72, 0xbfb8aa3b, v52
	v_mul_f32_e32 v73, 0xbfb8aa3b, v53
	v_exp_f32_e32 v70, v70
	v_exp_f32_e32 v71, v71
	v_exp_f32_e32 v72, v72
	v_exp_f32_e32 v73, v73
	v_add_f32_e32 v70, 1.0, v70
	v_add_f32_e32 v71, 1.0, v71
	v_add_f32_e32 v72, 1.0, v72
	v_add_f32_e32 v73, 1.0, v73
	v_rcp_f32_e32 v70, v70
	v_rcp_f32_e32 v71, v71
	v_rcp_f32_e32 v72, v72
	v_rcp_f32_e32 v73, v73
	v_pk_mul_f32 v[70:71], v[50:51], v[70:71]
	s_nop 0
	v_cvt_pk_bf16_f32 v242, v70, v71
	v_pk_mul_f32 v[72:73], v[52:53], v[72:73]
	s_nop 0
	v_cvt_pk_bf16_f32 v243, v72, v73
	s_nop 1
	v_permlane16_swap_b32_e32 v240, v242
	v_permlane16_swap_b32_e32 v241, v243
	v_lshl_add_u64 v[214:215], v[68:69], 0, v[226:227]
	global_store_dwordx4 v[214:215], v[240:243], off
	v_mul_f32_e32 v70, 0xbfb8aa3b, v46
	v_mul_f32_e32 v71, 0xbfb8aa3b, v47
	v_mul_f32_e32 v72, 0xbfb8aa3b, v48
	v_mul_f32_e32 v73, 0xbfb8aa3b, v49
	v_exp_f32_e32 v70, v70
	v_exp_f32_e32 v71, v71
	v_exp_f32_e32 v72, v72
	v_exp_f32_e32 v73, v73
	v_add_f32_e32 v70, 1.0, v70
	v_add_f32_e32 v71, 1.0, v71
	v_add_f32_e32 v72, 1.0, v72
	v_add_f32_e32 v73, 1.0, v73
	v_rcp_f32_e32 v70, v70
	v_rcp_f32_e32 v71, v71
	v_rcp_f32_e32 v72, v72
	v_rcp_f32_e32 v73, v73
	v_lshl_add_u64 v[68:69], v[66:67], 0, s[16:17]
	v_pk_mul_f32 v[70:71], v[46:47], v[70:71]
	s_mov_b32 s16, 0x10000
	v_pk_mul_f32 v[72:73], v[48:49], v[72:73]
	v_cvt_pk_bf16_f32 v244, v70, v71
	v_cvt_pk_bf16_f32 v245, v72, v73
	v_add_co_u32_e32 v72, vcc, s16, v66
	s_mov_b64 s[16:17], 0x18000
	s_nop 0
	v_addc_co_u32_e32 v73, vcc, 0, v67, vcc
	v_mul_f32_e32 v70, 0xbfb8aa3b, v42
	v_mul_f32_e32 v71, 0xbfb8aa3b, v43
	v_mul_f32_e32 v72, 0xbfb8aa3b, v44
	v_mul_f32_e32 v73, 0xbfb8aa3b, v45
	v_exp_f32_e32 v70, v70
	v_exp_f32_e32 v71, v71
	v_exp_f32_e32 v72, v72
	v_exp_f32_e32 v73, v73
	v_add_f32_e32 v70, 1.0, v70
	v_add_f32_e32 v71, 1.0, v71
	v_add_f32_e32 v72, 1.0, v72
	v_add_f32_e32 v73, 1.0, v73
	v_rcp_f32_e32 v70, v70
	v_rcp_f32_e32 v71, v71
	v_rcp_f32_e32 v72, v72
	v_rcp_f32_e32 v73, v73
	v_pk_mul_f32 v[70:71], v[42:43], v[70:71]
	s_nop 0
	v_cvt_pk_bf16_f32 v246, v70, v71
	v_pk_mul_f32 v[72:73], v[44:45], v[72:73]
	s_nop 0
	v_cvt_pk_bf16_f32 v247, v72, v73
	s_nop 1
	v_permlane16_swap_b32_e32 v244, v246
	v_permlane16_swap_b32_e32 v245, v247
	v_lshl_add_u64 v[216:217], v[68:69], 0, v[226:227]
	global_store_dwordx4 v[216:217], v[244:247], off
	v_mul_f32_e32 v70, 0xbfb8aa3b, v38
	v_mul_f32_e32 v71, 0xbfb8aa3b, v39
	v_mul_f32_e32 v72, 0xbfb8aa3b, v40
	v_mul_f32_e32 v73, 0xbfb8aa3b, v41
	v_exp_f32_e32 v70, v70
	v_exp_f32_e32 v71, v71
	v_exp_f32_e32 v72, v72
	v_exp_f32_e32 v73, v73
	v_add_f32_e32 v70, 1.0, v70
	v_add_f32_e32 v71, 1.0, v71
	v_add_f32_e32 v72, 1.0, v72
	v_add_f32_e32 v73, 1.0, v73
	v_rcp_f32_e32 v70, v70
	v_rcp_f32_e32 v71, v71
	v_rcp_f32_e32 v72, v72
	v_rcp_f32_e32 v73, v73
	v_lshl_add_u64 v[68:69], v[66:67], 0, s[16:17]
	v_pk_mul_f32 v[70:71], v[38:39], v[70:71]
	s_mov_b32 s16, 0x18000
	v_pk_mul_f32 v[72:73], v[40:41], v[72:73]
	v_cvt_pk_bf16_f32 v248, v70, v71
	v_cvt_pk_bf16_f32 v249, v72, v73
	v_add_co_u32_e32 v72, vcc, s16, v66
	s_mov_b64 s[16:17], 0x40000
	s_nop 0
	v_addc_co_u32_e32 v73, vcc, 0, v67, vcc
	v_mul_f32_e32 v70, 0xbfb8aa3b, v34
	v_mul_f32_e32 v71, 0xbfb8aa3b, v35
	v_mul_f32_e32 v72, 0xbfb8aa3b, v36
	v_mul_f32_e32 v73, 0xbfb8aa3b, v37
	v_exp_f32_e32 v70, v70
	v_exp_f32_e32 v71, v71
	v_exp_f32_e32 v72, v72
	v_exp_f32_e32 v73, v73
	v_add_f32_e32 v70, 1.0, v70
	v_add_f32_e32 v71, 1.0, v71
	v_add_f32_e32 v72, 1.0, v72
	v_add_f32_e32 v73, 1.0, v73
	v_rcp_f32_e32 v70, v70
	v_rcp_f32_e32 v71, v71
	v_rcp_f32_e32 v72, v72
	v_rcp_f32_e32 v73, v73
	v_pk_mul_f32 v[70:71], v[34:35], v[70:71]
	s_nop 0
	v_cvt_pk_bf16_f32 v250, v70, v71
	v_pk_mul_f32 v[72:73], v[36:37], v[72:73]
	s_nop 0
	v_cvt_pk_bf16_f32 v251, v72, v73
	s_nop 1
	v_permlane16_swap_b32_e32 v248, v250
	v_permlane16_swap_b32_e32 v249, v251
	v_lshl_add_u64 v[218:219], v[68:69], 0, v[226:227]
	global_store_dwordx4 v[218:219], v[248:251], off
	v_mul_f32_e32 v70, 0xbfb8aa3b, v30
	v_mul_f32_e32 v71, 0xbfb8aa3b, v31
	v_mul_f32_e32 v72, 0xbfb8aa3b, v32
	v_mul_f32_e32 v73, 0xbfb8aa3b, v33
	v_exp_f32_e32 v70, v70
	v_exp_f32_e32 v71, v71
	v_exp_f32_e32 v72, v72
	v_exp_f32_e32 v73, v73
	v_add_f32_e32 v70, 1.0, v70
	v_add_f32_e32 v71, 1.0, v71
	v_add_f32_e32 v72, 1.0, v72
	v_add_f32_e32 v73, 1.0, v73
	v_rcp_f32_e32 v70, v70
	v_rcp_f32_e32 v71, v71
	v_rcp_f32_e32 v72, v72
	v_rcp_f32_e32 v73, v73
	v_lshl_add_u64 v[68:69], v[66:67], 0, s[16:17]
	v_pk_mul_f32 v[70:71], v[30:31], v[70:71]
	s_mov_b32 s16, 0x40000
	v_pk_mul_f32 v[72:73], v[32:33], v[72:73]
	v_cvt_pk_bf16_f32 v228, v70, v71
	v_cvt_pk_bf16_f32 v229, v72, v73
	v_add_co_u32_e32 v72, vcc, s16, v66
	s_mov_b64 s[16:17], 0x48000
	s_nop 0
	v_addc_co_u32_e32 v73, vcc, 0, v67, vcc
	v_mul_f32_e32 v70, 0xbfb8aa3b, v26
	v_mul_f32_e32 v71, 0xbfb8aa3b, v27
	v_mul_f32_e32 v72, 0xbfb8aa3b, v28
	v_mul_f32_e32 v73, 0xbfb8aa3b, v29
	v_exp_f32_e32 v70, v70
	v_exp_f32_e32 v71, v71
	v_exp_f32_e32 v72, v72
	v_exp_f32_e32 v73, v73
	v_add_f32_e32 v70, 1.0, v70
	v_add_f32_e32 v71, 1.0, v71
	v_add_f32_e32 v72, 1.0, v72
	v_add_f32_e32 v73, 1.0, v73
	v_rcp_f32_e32 v70, v70
	v_rcp_f32_e32 v71, v71
	v_rcp_f32_e32 v72, v72
	v_rcp_f32_e32 v73, v73
	v_pk_mul_f32 v[70:71], v[26:27], v[70:71]
	s_nop 0
	v_cvt_pk_bf16_f32 v230, v70, v71
	v_pk_mul_f32 v[72:73], v[28:29], v[72:73]
	s_nop 0
	v_cvt_pk_bf16_f32 v231, v72, v73
	s_nop 1
	v_permlane16_swap_b32_e32 v228, v230
	v_permlane16_swap_b32_e32 v229, v231
	v_lshl_add_u64 v[214:215], v[68:69], 0, v[226:227]
	global_store_dwordx4 v[214:215], v[228:231], off
	v_mul_f32_e32 v70, 0xbfb8aa3b, v22
	v_mul_f32_e32 v71, 0xbfb8aa3b, v23
	v_mul_f32_e32 v72, 0xbfb8aa3b, v24
	v_mul_f32_e32 v73, 0xbfb8aa3b, v25
	v_exp_f32_e32 v70, v70
	v_exp_f32_e32 v71, v71
	v_exp_f32_e32 v72, v72
	v_exp_f32_e32 v73, v73
	v_add_f32_e32 v70, 1.0, v70
	v_add_f32_e32 v71, 1.0, v71
	v_add_f32_e32 v72, 1.0, v72
	v_add_f32_e32 v73, 1.0, v73
	v_rcp_f32_e32 v70, v70
	v_rcp_f32_e32 v71, v71
	v_rcp_f32_e32 v72, v72
	v_rcp_f32_e32 v73, v73
	v_lshl_add_u64 v[68:69], v[66:67], 0, s[16:17]
	v_pk_mul_f32 v[70:71], v[22:23], v[70:71]
	s_mov_b32 s16, 0x48000
	v_pk_mul_f32 v[72:73], v[24:25], v[72:73]
	v_cvt_pk_bf16_f32 v232, v70, v71
	v_cvt_pk_bf16_f32 v233, v72, v73
	v_add_co_u32_e32 v72, vcc, s16, v66
	s_mov_b64 s[16:17], 0x50000
	s_nop 0
	v_addc_co_u32_e32 v73, vcc, 0, v67, vcc
	v_mul_f32_e32 v70, 0xbfb8aa3b, v18
	v_mul_f32_e32 v71, 0xbfb8aa3b, v19
	v_mul_f32_e32 v72, 0xbfb8aa3b, v20
	v_mul_f32_e32 v73, 0xbfb8aa3b, v21
	v_exp_f32_e32 v70, v70
	v_exp_f32_e32 v71, v71
	v_exp_f32_e32 v72, v72
	v_exp_f32_e32 v73, v73
	v_add_f32_e32 v70, 1.0, v70
	v_add_f32_e32 v71, 1.0, v71
	v_add_f32_e32 v72, 1.0, v72
	v_add_f32_e32 v73, 1.0, v73
	v_rcp_f32_e32 v70, v70
	v_rcp_f32_e32 v71, v71
	v_rcp_f32_e32 v72, v72
	v_rcp_f32_e32 v73, v73
	v_pk_mul_f32 v[70:71], v[18:19], v[70:71]
	s_nop 0
	v_cvt_pk_bf16_f32 v234, v70, v71
	v_pk_mul_f32 v[72:73], v[20:21], v[72:73]
	s_nop 0
	v_cvt_pk_bf16_f32 v235, v72, v73
	s_nop 1
	v_permlane16_swap_b32_e32 v232, v234
	v_permlane16_swap_b32_e32 v233, v235
	v_lshl_add_u64 v[216:217], v[68:69], 0, v[226:227]
	global_store_dwordx4 v[216:217], v[232:235], off
	v_mul_f32_e32 v70, 0xbfb8aa3b, v14
	v_mul_f32_e32 v71, 0xbfb8aa3b, v15
	v_mul_f32_e32 v72, 0xbfb8aa3b, v16
	v_mul_f32_e32 v73, 0xbfb8aa3b, v17
	v_exp_f32_e32 v70, v70
	v_exp_f32_e32 v71, v71
	v_exp_f32_e32 v72, v72
	v_exp_f32_e32 v73, v73
	v_add_f32_e32 v70, 1.0, v70
	v_add_f32_e32 v71, 1.0, v71
	v_add_f32_e32 v72, 1.0, v72
	v_add_f32_e32 v73, 1.0, v73
	v_rcp_f32_e32 v70, v70
	v_rcp_f32_e32 v71, v71
	v_rcp_f32_e32 v72, v72
	v_rcp_f32_e32 v73, v73
	v_lshl_add_u64 v[68:69], v[66:67], 0, s[16:17]
	v_pk_mul_f32 v[70:71], v[14:15], v[70:71]
	s_mov_b32 s16, 0x50000
	v_pk_mul_f32 v[72:73], v[16:17], v[72:73]
	v_cvt_pk_bf16_f32 v236, v70, v71
	v_cvt_pk_bf16_f32 v237, v72, v73
	v_add_co_u32_e32 v72, vcc, s16, v66
	s_mov_b64 s[16:17], 0x58000
	s_nop 0
	v_addc_co_u32_e32 v73, vcc, 0, v67, vcc
	v_mul_f32_e32 v70, 0xbfb8aa3b, v8
	v_mul_f32_e32 v71, 0xbfb8aa3b, v9
	v_mul_f32_e32 v72, 0xbfb8aa3b, v10
	v_mul_f32_e32 v73, 0xbfb8aa3b, v11
	v_exp_f32_e32 v70, v70
	v_exp_f32_e32 v71, v71
	v_exp_f32_e32 v72, v72
	v_exp_f32_e32 v73, v73
	v_add_f32_e32 v70, 1.0, v70
	v_add_f32_e32 v71, 1.0, v71
	v_add_f32_e32 v72, 1.0, v72
	v_add_f32_e32 v73, 1.0, v73
	v_rcp_f32_e32 v70, v70
	v_rcp_f32_e32 v71, v71
	v_rcp_f32_e32 v72, v72
	v_rcp_f32_e32 v73, v73
	v_pk_mul_f32 v[70:71], v[8:9], v[70:71]
	s_nop 0
	v_cvt_pk_bf16_f32 v238, v70, v71
	v_pk_mul_f32 v[72:73], v[10:11], v[72:73]
	s_nop 0
	v_cvt_pk_bf16_f32 v239, v72, v73
	s_nop 1
	v_permlane16_swap_b32_e32 v236, v238
	v_permlane16_swap_b32_e32 v237, v239
	v_lshl_add_u64 v[218:219], v[68:69], 0, v[226:227]
	global_store_dwordx4 v[218:219], v[236:239], off
	v_mul_f32_e32 v70, 0xbfb8aa3b, v4
	v_mul_f32_e32 v71, 0xbfb8aa3b, v5
	v_mul_f32_e32 v72, 0xbfb8aa3b, v6
	v_mul_f32_e32 v73, 0xbfb8aa3b, v7
	v_exp_f32_e32 v70, v70
	v_exp_f32_e32 v71, v71
	v_exp_f32_e32 v72, v72
	v_exp_f32_e32 v73, v73
	v_add_f32_e32 v70, 1.0, v70
	v_add_f32_e32 v71, 1.0, v71
	v_add_f32_e32 v72, 1.0, v72
	v_add_f32_e32 v73, 1.0, v73
	v_rcp_f32_e32 v70, v70
	v_rcp_f32_e32 v71, v71
	v_rcp_f32_e32 v72, v72
	v_rcp_f32_e32 v73, v73
	v_lshl_add_u64 v[68:69], v[66:67], 0, s[16:17]
	s_mov_b32 s16, 0x58000
	v_pk_mul_f32 v[70:71], v[4:5], v[70:71]
	v_pk_mul_f32 v[72:73], v[6:7], v[72:73]
	v_add_co_u32_e32 v66, vcc, s16, v66
	v_cvt_pk_bf16_f32 v240, v70, v71
	v_cvt_pk_bf16_f32 v241, v72, v73
	v_addc_co_u32_e32 v67, vcc, 0, v67, vcc
	v_mul_f32_e32 v66, 0xbfb8aa3b, v0
	v_mul_f32_e32 v67, 0xbfb8aa3b, v1
	v_mul_f32_e32 v70, 0xbfb8aa3b, v2
	v_mul_f32_e32 v71, 0xbfb8aa3b, v3
	v_exp_f32_e32 v66, v66
	v_exp_f32_e32 v67, v67
	v_exp_f32_e32 v70, v70
	v_exp_f32_e32 v71, v71
	v_add_f32_e32 v66, 1.0, v66
	v_add_f32_e32 v67, 1.0, v67
	v_add_f32_e32 v70, 1.0, v70
	v_add_f32_e32 v71, 1.0, v71
	v_rcp_f32_e32 v66, v66
	v_rcp_f32_e32 v67, v67
	v_rcp_f32_e32 v70, v70
	v_rcp_f32_e32 v71, v71
	v_pk_mul_f32 v[66:67], v[0:1], v[66:67]
	s_nop 0
	v_cvt_pk_bf16_f32 v242, v66, v67
	v_pk_mul_f32 v[70:71], v[2:3], v[70:71]
	s_nop 0
	v_cvt_pk_bf16_f32 v243, v70, v71
	s_nop 1
	v_permlane16_swap_b32_e32 v240, v242
	v_permlane16_swap_b32_e32 v241, v243
	v_lshl_add_u64 v[214:215], v[68:69], 0, v[226:227]
	global_store_dwordx4 v[214:215], v[240:243], off

.LBB0_421:
	s_andn2_b64 vcc, exec, s[60:61]
	s_cbranch_vccnz .LBB0_429
	s_ashr_i32 s60, s41, 1
	s_ashr_i32 s61, s60, 31
	s_lshl_b64 s[16:17], s[60:61], 25
	s_add_u32 s16, s50, s16
	s_addc_u32 s17, s51, s17
	s_cmp_lt_u32 s41, 2
	s_cselect_b64 vcc, -1, 0
	s_and_b32 s25, s53, 0x1e0
	v_mov_b32_e32 v66, 0x3e38aa3b
	v_add_u32_e32 v68, s25, v138
	v_cndmask_b32_e32 v66, 1.0, v66, vcc
	v_ashrrev_i32_e32 v69, 31, v68
	v_lshl_add_u64 v[68:69], v[68:69], 1, s[16:17]
	v_lshlrev_b64 v[70:71], 10, v[136:137]
	s_waitcnt lgkmcnt(0)
	v_pk_mul_f32 v[64:65], v[66:67], v[64:65] op_sel_hi:[0,1]
	v_pk_mul_f32 v[62:63], v[66:67], v[62:63] op_sel_hi:[0,1]
	v_lshl_add_u64 v[68:69], v[68:69], 0, v[70:71]
	v_cvt_pk_bf16_f32 v244, v62, v63
	v_cvt_pk_bf16_f32 v245, v64, v65
	v_pk_mul_f32 v[60:61], v[66:67], v[60:61] op_sel_hi:[0,1]
	v_pk_mul_f32 v[58:59], v[66:67], v[58:59] op_sel_hi:[0,1]
	v_cvt_pk_bf16_f32 v246, v58, v59
	v_cvt_pk_bf16_f32 v247, v60, v61
	s_mov_b64 s[16:17], 0x4000
	s_nop 1
	v_permlane16_swap_b32_e32 v244, v246
	v_permlane16_swap_b32_e32 v245, v247
	v_lshl_add_u64 v[216:217], v[68:69], 0, v[226:227]
	global_store_dwordx4 v[216:217], v[244:247], off
	v_lshl_add_u64 v[70:71], v[68:69], 0, s[16:17]
	s_movk_i32 s16, 0x4000
	v_pk_mul_f32 v[56:57], v[66:67], v[56:57] op_sel_hi:[0,1]
	v_pk_mul_f32 v[54:55], v[66:67], v[54:55] op_sel_hi:[0,1]
	v_add_co_u32_e32 v74, vcc, s16, v68
	v_cvt_pk_bf16_f32 v248, v54, v55
	v_cvt_pk_bf16_f32 v249, v56, v57
	v_addc_co_u32_e32 v75, vcc, 0, v69, vcc
	v_pk_mul_f32 v[52:53], v[66:67], v[52:53] op_sel_hi:[0,1]
	v_pk_mul_f32 v[50:51], v[66:67], v[50:51] op_sel_hi:[0,1]
	v_cvt_pk_bf16_f32 v250, v50, v51
	v_cvt_pk_bf16_f32 v251, v52, v53
	s_mov_b64 s[16:17], 0x8000
	s_nop 1
	v_permlane16_swap_b32_e32 v248, v250
	v_permlane16_swap_b32_e32 v249, v251
	v_lshl_add_u64 v[218:219], v[70:71], 0, v[226:227]
	global_store_dwordx4 v[218:219], v[248:251], off
	v_lshl_add_u64 v[70:71], v[68:69], 0, s[16:17]
	s_mov_b32 s16, 0x8000
	v_pk_mul_f32 v[48:49], v[66:67], v[48:49] op_sel_hi:[0,1]
	v_pk_mul_f32 v[46:47], v[66:67], v[46:47] op_sel_hi:[0,1]
	v_add_co_u32_e32 v74, vcc, s16, v68
	v_cvt_pk_bf16_f32 v228, v46, v47
	v_cvt_pk_bf16_f32 v229, v48, v49
	v_addc_co_u32_e32 v75, vcc, 0, v69, vcc
	v_pk_mul_f32 v[44:45], v[66:67], v[44:45] op_sel_hi:[0,1]
	v_pk_mul_f32 v[42:43], v[66:67], v[42:43] op_sel_hi:[0,1]
	v_cvt_pk_bf16_f32 v230, v42, v43
	v_cvt_pk_bf16_f32 v231, v44, v45
	s_mov_b64 s[16:17], 0xc000
	s_nop 1
	v_permlane16_swap_b32_e32 v228, v230
	v_permlane16_swap_b32_e32 v229, v231
	v_lshl_add_u64 v[214:215], v[70:71], 0, v[226:227]
	global_store_dwordx4 v[214:215], v[228:231], off
	v_lshl_add_u64 v[70:71], v[68:69], 0, s[16:17]
	s_mov_b32 s16, 0xc000
	v_pk_mul_f32 v[40:41], v[66:67], v[40:41] op_sel_hi:[0,1]
	v_pk_mul_f32 v[38:39], v[66:67], v[38:39] op_sel_hi:[0,1]
	v_add_co_u32_e32 v74, vcc, s16, v68
	v_cvt_pk_bf16_f32 v232, v38, v39
	v_cvt_pk_bf16_f32 v233, v40, v41
	v_addc_co_u32_e32 v75, vcc, 0, v69, vcc
	v_pk_mul_f32 v[36:37], v[66:67], v[36:37] op_sel_hi:[0,1]
	v_pk_mul_f32 v[34:35], v[66:67], v[34:35] op_sel_hi:[0,1]
	s_mov_b32 s16, 0x20000
	v_cvt_pk_bf16_f32 v234, v34, v35
	v_cvt_pk_bf16_f32 v235, v36, v37
	v_pk_mul_f32 v[32:33], v[66:67], v[32:33] op_sel_hi:[0,1]
	v_pk_mul_f32 v[30:31], v[66:67], v[30:31] op_sel_hi:[0,1]
	v_add_co_u32_e32 v74, vcc, s16, v68
	s_nop 1
	v_permlane16_swap_b32_e32 v232, v234
	v_permlane16_swap_b32_e32 v233, v235
	v_lshl_add_u64 v[216:217], v[70:71], 0, v[226:227]
	global_store_dwordx4 v[216:217], v[232:235], off
	v_cvt_pk_bf16_f32 v236, v30, v31
	v_cvt_pk_bf16_f32 v237, v32, v33
	v_addc_co_u32_e32 v75, vcc, 0, v69, vcc
	v_pk_mul_f32 v[28:29], v[66:67], v[28:29] op_sel_hi:[0,1]
	v_pk_mul_f32 v[26:27], v[66:67], v[26:27] op_sel_hi:[0,1]
	v_lshl_add_u64 v[70:71], v[68:69], 0, s[46:47]
	v_cvt_pk_bf16_f32 v238, v26, v27
	v_cvt_pk_bf16_f32 v239, v28, v29
	s_mov_b64 s[16:17], 0x24000
	s_nop 1
	v_permlane16_swap_b32_e32 v236, v238
	v_permlane16_swap_b32_e32 v237, v239
	v_lshl_add_u64 v[218:219], v[70:71], 0, v[226:227]
	global_store_dwordx4 v[218:219], v[236:239], off
	v_lshl_add_u64 v[70:71], v[68:69], 0, s[16:17]
	s_mov_b32 s16, 0x24000
	v_pk_mul_f32 v[24:25], v[66:67], v[24:25] op_sel_hi:[0,1]
	v_pk_mul_f32 v[22:23], v[66:67], v[22:23] op_sel_hi:[0,1]
	v_add_co_u32_e32 v74, vcc, s16, v68
	v_cvt_pk_bf16_f32 v240, v22, v23
	v_cvt_pk_bf16_f32 v241, v24, v25
	v_addc_co_u32_e32 v75, vcc, 0, v69, vcc
	v_pk_mul_f32 v[20:21], v[66:67], v[20:21] op_sel_hi:[0,1]
	v_pk_mul_f32 v[18:19], v[66:67], v[18:19] op_sel_hi:[0,1]
	v_cvt_pk_bf16_f32 v242, v18, v19
	v_cvt_pk_bf16_f32 v243, v20, v21
	s_mov_b64 s[16:17], 0x28000
	s_nop 1
	v_permlane16_swap_b32_e32 v240, v242
	v_permlane16_swap_b32_e32 v241, v243
	v_lshl_add_u64 v[214:215], v[70:71], 0, v[226:227]
	global_store_dwordx4 v[214:215], v[240:243], off
	v_lshl_add_u64 v[70:71], v[68:69], 0, s[16:17]
	s_mov_b32 s16, 0x28000
	v_pk_mul_f32 v[16:17], v[66:67], v[16:17] op_sel_hi:[0,1]
	v_pk_mul_f32 v[14:15], v[66:67], v[14:15] op_sel_hi:[0,1]
	v_add_co_u32_e32 v74, vcc, s16, v68
	v_cvt_pk_bf16_f32 v244, v14, v15
	v_cvt_pk_bf16_f32 v245, v16, v17
	v_addc_co_u32_e32 v75, vcc, 0, v69, vcc
	v_pk_mul_f32 v[10:11], v[66:67], v[10:11] op_sel_hi:[0,1]
	v_pk_mul_f32 v[8:9], v[66:67], v[8:9] op_sel_hi:[0,1]
	v_cvt_pk_bf16_f32 v246, v8, v9
	v_cvt_pk_bf16_f32 v247, v10, v11
	s_mov_b64 s[16:17], 0x2c000
	s_nop 1
	v_permlane16_swap_b32_e32 v244, v246
	v_permlane16_swap_b32_e32 v245, v247
	v_lshl_add_u64 v[216:217], v[70:71], 0, v[226:227]
	global_store_dwordx4 v[216:217], v[244:247], off
	v_lshl_add_u64 v[70:71], v[68:69], 0, s[16:17]
	s_mov_b32 s16, 0x2c000
	v_pk_mul_f32 v[6:7], v[66:67], v[6:7] op_sel_hi:[0,1]
	v_pk_mul_f32 v[4:5], v[66:67], v[4:5] op_sel_hi:[0,1]
	v_add_co_u32_e32 v68, vcc, s16, v68
	v_pk_mul_f32 v[2:3], v[66:67], v[2:3] op_sel_hi:[0,1]
	v_pk_mul_f32 v[0:1], v[66:67], v[0:1] op_sel_hi:[0,1]
	v_cvt_pk_bf16_f32 v248, v4, v5
	v_cvt_pk_bf16_f32 v249, v6, v7
	v_addc_co_u32_e32 v69, vcc, 0, v69, vcc
	v_cvt_pk_bf16_f32 v250, v0, v1
	v_cvt_pk_bf16_f32 v251, v2, v3
	s_cmp_gt_i32 s60, 1
	s_nop 1
	v_permlane16_swap_b32_e32 v248, v250
	v_permlane16_swap_b32_e32 v249, v251
	v_lshl_add_u64 v[218:219], v[70:71], 0, v[226:227]
	global_store_dwordx4 v[218:219], v[248:251], off
	s_cbranch_scc1 .LBB0_429
	v_mul_f32_e32 v63, v63, v63
	v_mul_f32_e32 v59, v59, v59
	v_mul_f32_e32 v55, v55, v55
	v_mul_f32_e32 v51, v51, v51
	v_fmac_f32_e32 v63, v62, v62
	v_mul_f32_e32 v62, v65, v65
	v_fmac_f32_e32 v59, v58, v58
	v_mul_f32_e32 v58, v61, v61
	v_fmac_f32_e32 v55, v54, v54
	v_mul_f32_e32 v54, v57, v57
	v_fmac_f32_e32 v51, v50, v50
	v_mul_f32_e32 v50, v53, v53
	v_mul_f32_e32 v47, v47, v47
	v_mul_f32_e32 v43, v43, v43
	v_mul_f32_e32 v39, v39, v39
	v_mul_f32_e32 v35, v35, v35
	v_fmac_f32_e32 v62, v64, v64
	v_fmac_f32_e32 v58, v60, v60
	v_fmac_f32_e32 v54, v56, v56
	v_fmac_f32_e32 v50, v52, v52
	v_fmac_f32_e32 v47, v46, v46
	v_mul_f32_e32 v46, v49, v49
	v_fmac_f32_e32 v43, v42, v42
	v_mul_f32_e32 v42, v45, v45
	v_fmac_f32_e32 v39, v38, v38
	v_mul_f32_e32 v38, v41, v41
	v_fmac_f32_e32 v35, v34, v34
	v_mul_f32_e32 v34, v37, v37
	v_mul_f32_e32 v31, v31, v31
	v_mul_f32_e32 v27, v27, v27
	v_mul_f32_e32 v23, v23, v23
	v_mul_f32_e32 v19, v19, v19
	v_add_f32_e32 v62, v63, v62
	v_add_f32_e32 v58, v59, v58
	v_add_f32_e32 v54, v55, v54
	v_add_f32_e32 v50, v51, v50
	v_fmac_f32_e32 v46, v48, v48
	v_fmac_f32_e32 v42, v44, v44
	v_fmac_f32_e32 v38, v40, v40
	v_fmac_f32_e32 v34, v36, v36
	v_fmac_f32_e32 v31, v30, v30
	v_mul_f32_e32 v30, v33, v33
	v_fmac_f32_e32 v27, v26, v26
	v_mul_f32_e32 v26, v29, v29
	v_fmac_f32_e32 v23, v22, v22
	v_mul_f32_e32 v22, v25, v25
	v_fmac_f32_e32 v19, v18, v18
	v_mul_f32_e32 v18, v21, v21
	v_mul_f32_e32 v15, v15, v15
	v_mul_f32_e32 v9, v9, v9
	v_mul_f32_e32 v5, v5, v5
	v_mul_f32_e32 v1, v1, v1
	v_add_f32_e32 v58, v62, v58
	v_add_f32_e32 v50, v54, v50
	v_add_f32_e32 v46, v47, v46
	v_add_f32_e32 v42, v43, v42
	v_add_f32_e32 v38, v39, v38
	v_add_f32_e32 v34, v35, v34
	v_fmac_f32_e32 v30, v32, v32
	v_fmac_f32_e32 v26, v28, v28
	v_fmac_f32_e32 v22, v24, v24
	v_fmac_f32_e32 v18, v20, v20
	v_fmac_f32_e32 v15, v14, v14
	v_mul_f32_e32 v14, v17, v17
	v_fmac_f32_e32 v9, v8, v8
	v_mul_f32_e32 v8, v11, v11
	v_fmac_f32_e32 v5, v4, v4
	v_mul_f32_e32 v4, v7, v7
	v_fmac_f32_e32 v1, v0, v0
	v_mul_f32_e32 v0, v3, v3
	ds_bpermute_b32 v59, v155, v58
	ds_bpermute_b32 v51, v155, v50
	v_add_f32_e32 v42, v46, v42
	v_add_f32_e32 v34, v38, v34
	v_add_f32_e32 v30, v31, v30
	v_add_f32_e32 v26, v27, v26
	v_add_f32_e32 v22, v23, v22
	v_add_f32_e32 v18, v19, v18
	v_fmac_f32_e32 v14, v16, v16
	v_fmac_f32_e32 v8, v10, v10
	v_fmac_f32_e32 v4, v6, v6
	v_fmac_f32_e32 v0, v2, v2
	ds_bpermute_b32 v43, v155, v42
	ds_bpermute_b32 v35, v155, v34
	v_add_f32_e32 v26, v30, v26
	v_add_f32_e32 v18, v22, v18
	v_add_f32_e32 v14, v15, v14
	v_add_f32_e32 v8, v9, v8
	v_add_f32_e32 v4, v5, v4
	v_add_f32_e32 v0, v1, v0
	ds_bpermute_b32 v27, v155, v26
	ds_bpermute_b32 v19, v155, v18
	v_add_f32_e32 v8, v14, v8
	v_add_f32_e32 v0, v4, v0
	ds_bpermute_b32 v9, v155, v8
	ds_bpermute_b32 v1, v155, v0
	s_waitcnt lgkmcnt(0)
	v_add_f32_e32 v52, v58, v59
	v_add_f32_e32 v50, v50, v51
	ds_bpermute_b32 v53, v154, v52
	ds_bpermute_b32 v51, v154, v50
	v_add_f32_e32 v38, v42, v43
	v_add_f32_e32 v34, v34, v35
	ds_bpermute_b32 v39, v154, v38
	ds_bpermute_b32 v35, v154, v34
	v_add_f32_e32 v26, v26, v27
	v_add_f32_e32 v2, v18, v19
	ds_bpermute_b32 v27, v154, v26
	ds_bpermute_b32 v3, v154, v2
	v_add_f32_e32 v4, v8, v9
	v_add_f32_e32 v0, v0, v1
	ds_bpermute_b32 v5, v154, v4
	ds_bpermute_b32 v1, v154, v0
	s_waitcnt lgkmcnt(0)
	v_add_f32_e32 v36, v52, v53
	v_add_f32_e32 v37, v50, v51
	v_max3_f32 v28, v36, 0, v37
	v_add_f32_e32 v29, v38, v39
	v_add_f32_e32 v30, v34, v35
	v_max3_f32 v28, v28, v29, v30
	v_add_f32_e32 v6, v26, v27
	v_add_f32_e32 v2, v2, v3
	v_max3_f32 v2, v28, v6, v2
	v_add_f32_e32 v3, v4, v5
	v_add_f32_e32 v0, v0, v1
	v_max3_f32 v0, v2, v3, v0
	ds_bpermute_b32 v1, v157, v0
	s_waitcnt lgkmcnt(0)
	v_max_f32_e32 v1, v1, v1
	v_max_f32_e32 v0, v0, v1
	ds_bpermute_b32 v1, v149, v0
	s_waitcnt lgkmcnt(0)
	v_max_f32_e32 v1, v1, v1
	v_max_f32_e32 v0, v0, v1
	ds_bpermute_b32 v1, v148, v0
	s_waitcnt lgkmcnt(0)
	v_max_f32_e32 v1, v1, v1
	v_max_f32_e32 v0, v0, v1
	ds_bpermute_b32 v1, v156, v0
	s_and_saveexec_b64 s[62:63], s[4:5]
	s_cbranch_execz .LBB0_428
	s_waitcnt lgkmcnt(0)
	v_max_f32_e32 v1, v1, v1
	v_max_f32_e32 v0, v0, v0
	s_mov_b64 s[4:5], exec
	v_max_f32_e32 v0, v0, v1
	s_mov_b32 s16, 0
